# attention tile loop: common path straightened (rare/PV-only/head-DMA blocks out of line, wait-selection diamonds collapsed, scalar guards for V loads), remaining DMA sites to scalar-base form
# speedup vs baseline: 1.0058x; 1.0058x over previous
.LBB0_164:
	s_add_i32 s22, s23, -1
	s_cmp_lt_u32 s22, s16
	s_cselect_b64 s[88:89], -1, 0
	s_cmp_ge_u32 s22, s16
	s_cselect_b64 s[86:87], -1, 0
	s_waitcnt vmcnt(2)
.LBB0_168:
	s_lshl_b32 s101, s33, 14
	s_nop 1
	v_add_u32_e32 v82, s101, v239
	v_add_u32_e32 v102, s101, v240
	ds_read_b128 v[98:101], v82
	ds_read_b128 v[114:117], v82 offset:8192
	ds_read_b128 v[118:121], v102
	s_barrier
	s_cmp_lt_u32 s22, s19
	s_cbranch_scc0 .Lhd_u1e
.LBB0_174:
	s_lshl_b32 s22, s49, 14
	s_add_i32 s54, s22, 0
	s_cmp_ge_u32 s23, s19
	v_add_u32_e32 v249, s54, v244
	v_add_u32_e32 v212, s54, v245
	s_cbranch_scc1 .Lpvo_u1e
.LBB0_185:
	s_lshl_b32 s22, s33, 14
	s_add_i32 s22, s22, 0
	s_nop 1
	ds_read_b128 v[126:129], v249 offset:49152
	s_waitcnt lgkmcnt(1)
	v_mfma_f32_32x32x16_bf16 v[82:97], v[98:101], v[146:149], v[66:81]
	ds_read_b128 v[122:125], v102 offset:8192
	v_mfma_f32_32x32x16_bf16 v[98:113], v[114:117], v[146:149], v[66:81]
	v_add_u32_e32 v139, s22, v241
	ds_read_b128 v[114:117], v139
	v_mfma_f32_32x32x16_bf16 v[82:97], v[118:121], v[150:153], v[82:97]
	ds_read_b128 v[118:121], v139 offset:8192
	s_waitcnt lgkmcnt(0)
	v_mfma_f32_32x32x16_bf16 v[98:113], v[122:125], v[150:153], v[98:113]
	v_add_u32_e32 v139, s22, v243
	ds_read_b128 v[122:125], v139
	v_mfma_f32_32x32x16_bf16 v[82:97], v[114:117], v[154:157], v[82:97]
	ds_read_b128 v[114:117], v139 offset:8192
	v_mfma_f32_32x32x16_bf16 v[98:113], v[118:121], v[154:157], v[98:113]
	s_waitcnt lgkmcnt(0)
	v_mfma_f32_32x32x16_bf16 v[82:97], v[122:125], v[158:161], v[82:97]
	v_mfma_f32_32x32x16_bf16 v[98:113], v[114:117], v[158:161], v[98:113]
	s_nop 0
	ds_read_b128 v[122:125], v249 offset:53248
	ds_read_b128 v[118:121], v249 offset:57344
	ds_read_b128 v[114:117], v249 offset:61440
	s_add_i32 s22, s21, 64
	s_cmp_le_u32 s22, s20
	s_cbranch_scc1 .LBB0_188
	v_add_u32_e32 v130, s21, v248
	v_add_u32_e32 v130, 0x11f, v130
	v_and_b32_e32 v130, 0x3ffffffc, v130
	v_lshl_add_u32 v166, v130, 2, v0
	ds_read_b128 v[130:133], v166
	ds_read_b128 v[134:137], v166 offset:16
	ds_read_b128 v[138:141], v166 offset:64
	ds_read_b128 v[142:145], v166 offset:80
	s_waitcnt lgkmcnt(0)
	v_pk_add_f32 v[84:85], v[84:85], v[132:133]
	v_pk_add_f32 v[86:87], v[86:87], v[134:135]
	v_pk_add_f32 v[90:91], v[90:91], v[138:139]
	v_pk_add_f32 v[94:95], v[94:95], v[142:143]
	v_pk_add_f32 v[96:97], v[96:97], v[144:145]
	v_pk_add_f32 v[92:93], v[92:93], v[140:141]
	v_pk_add_f32 v[88:89], v[88:89], v[136:137]
	v_pk_add_f32 v[82:83], v[82:83], v[130:131]
	ds_read_b128 v[130:133], v166 offset:128
	ds_read_b128 v[134:137], v166 offset:144
	ds_read_b128 v[138:141], v166 offset:192
	ds_read_b128 v[142:145], v166 offset:208
	s_waitcnt lgkmcnt(0)
	v_pk_add_f32 v[100:101], v[100:101], v[132:133]
	v_pk_add_f32 v[102:103], v[102:103], v[134:135]
	v_pk_add_f32 v[106:107], v[106:107], v[138:139]
	v_pk_add_f32 v[110:111], v[110:111], v[142:143]
	v_pk_add_f32 v[112:113], v[112:113], v[144:145]
	v_pk_add_f32 v[108:109], v[108:109], v[140:141]
	v_pk_add_f32 v[104:105], v[104:105], v[136:137]
	v_pk_add_f32 v[98:99], v[98:99], v[130:131]

.LBB0_192:
	s_waitcnt lgkmcnt(3)
	v_mfma_f32_32x32x16_bf16 v[18:33], v[118:121], v[170:173], v[18:33]
	ds_read_b128 v[118:121], v130 offset:57344
	v_exp_f32_e32 v133, v94
	v_exp_f32_e32 v134, v95
	v_add_f32_e32 v131, v131, v133
	v_add_f32_e32 v132, v132, v134
	v_cvt_pk_bf16_f32 v176, v133, v134
	s_waitcnt lgkmcnt(3)
	v_mfma_f32_32x32x16_bf16 v[2:17], v[114:117], v[170:173], v[2:17]
	ds_read_b128 v[114:117], v130 offset:61440
	v_exp_f32_e32 v130, v96
	v_exp_f32_e32 v133, v97
	v_add_f32_e32 v131, v131, v130
	v_add_f32_e32 v132, v132, v133
	v_cvt_pk_bf16_f32 v177, v130, v133
	s_waitcnt lgkmcnt(3)
	v_mfma_f32_32x32x16_bf16 v[34:49], v[126:129], v[178:181], v[34:49]
	v_add_u32_e32 v130, s54, v247
	ds_read_b128 v[126:129], v130 offset:49152
	v_exp_f32_e32 v133, v98
	v_exp_f32_e32 v134, v99
	v_add_f32_e32 v131, v131, v133
	v_add_f32_e32 v132, v132, v134
	v_cvt_pk_bf16_f32 v182, v133, v134
	s_waitcnt lgkmcnt(3)
	v_mfma_f32_32x32x16_bf16 v[50:65], v[122:125], v[178:181], v[50:65]
	v_exp_f32_e32 v133, v100
	v_exp_f32_e32 v134, v101
	ds_read_b128 v[122:125], v130 offset:53248
	v_add_f32_e32 v131, v131, v133
	v_add_f32_e32 v132, v132, v134
	v_cvt_pk_bf16_f32 v183, v133, v134
	s_cmp_eq_u64 s[88:89], 0
	s_cbranch_scc1 .LBB0_194
	s_lshl_b32 s26, s31, 14
	s_add_i32 s26, s11, s26
	s_add_i32 m0, s26, 0xc000
	s_add_u32 s100, s8, s96
	s_addc_u32 s101, s9, s97
	global_load_lds_dwordx4 v216, s[100:101]
.LBB0_194:
	s_waitcnt lgkmcnt(3)
	v_mfma_f32_32x32x16_bf16 v[18:33], v[118:121], v[178:181], v[18:33]
	ds_read_b128 v[118:121], v130 offset:57344
	v_exp_f32_e32 v133, v102
	v_exp_f32_e32 v134, v103
	v_add_f32_e32 v131, v131, v133
	v_add_f32_e32 v132, v132, v134
	v_cvt_pk_bf16_f32 v184, v133, v134
	s_waitcnt lgkmcnt(3)
	v_mfma_f32_32x32x16_bf16 v[2:17], v[114:117], v[178:181], v[2:17]
	ds_read_b128 v[114:117], v130 offset:61440
	v_exp_f32_e32 v130, v104
	v_exp_f32_e32 v133, v105
	v_add_f32_e32 v131, v131, v130
	v_add_f32_e32 v132, v132, v133
	v_cvt_pk_bf16_f32 v185, v130, v133
	s_waitcnt lgkmcnt(3)
	v_mfma_f32_32x32x16_bf16 v[34:49], v[126:129], v[186:189], v[34:49]
	v_exp_f32_e32 v126, v106
	v_exp_f32_e32 v127, v107
	v_add_f32_e32 v128, v131, v126
	v_add_f32_e32 v129, v132, v127
	v_cvt_pk_bf16_f32 v190, v126, v127
	s_waitcnt lgkmcnt(2)
	v_mfma_f32_32x32x16_bf16 v[50:65], v[122:125], v[186:189], v[50:65]
	v_exp_f32_e32 v124, v108
	v_exp_f32_e32 v125, v109
	v_add_f32_e32 v122, v128, v124
	v_add_f32_e32 v123, v129, v125
	s_cmp_eq_u64 s[88:89], 0
	v_cvt_pk_bf16_f32 v191, v124, v125
	s_cbranch_scc1 .LBB0_196
	s_lshl_b32 s26, s31, 14
	s_add_i32 s26, s11, s26
	s_add_i32 m0, s26, 0xe000
	s_add_u32 s100, s8, s58
	s_addc_u32 s101, s9, s59
	global_load_lds_dwordx4 v216, s[100:101]
.LBB0_196:
	s_waitcnt lgkmcnt(1)
	v_mfma_f32_32x32x16_bf16 v[18:33], v[118:121], v[186:189], v[18:33]
	v_exp_f32_e32 v118, v110
	v_exp_f32_e32 v119, v111
	v_add_f32_e32 v120, v122, v118
	v_add_f32_e32 v121, v123, v119
	v_cvt_pk_bf16_f32 v192, v118, v119
	s_waitcnt lgkmcnt(0)
	v_mfma_f32_32x32x16_bf16 v[2:17], v[114:117], v[186:189], v[2:17]
	v_exp_f32_e32 v114, v112
	v_exp_f32_e32 v115, v113
	v_add_f32_e32 v116, v120, v114
	v_add_f32_e32 v117, v121, v115
	v_cvt_pk_bf16_f32 v193, v114, v115
	v_add_f32_e32 v212, v116, v117
	v_cmp_nge_f32_e32 vcc, s7, v212
	s_cbranch_vccnz .Lrare_u1e

.LBB0_200:
	s_cmp_lt_u32 s22, s17
	s_cselect_b64 s[88:89], -1, 0
	s_cmp_ge_u32 s22, s17
	s_cbranch_scc1 .Lotail_u1o
.Low2_u1o:
	s_waitcnt vmcnt(2)
.LBB0_208:
	s_add_i32 s26, s33, 1
	s_cmp_lg_u32 s33, 2
	s_cselect_b32 s33, s26, 0
	s_add_i32 s26, s48, 1
	s_cmp_lg_u32 s48, 2
	s_cselect_b32 s48, s26, 0
	s_add_i32 s26, s49, 1
	s_cmp_lg_u32 s49, 2
	s_cselect_b32 s49, s26, 0
	s_add_i32 s26, s31, 1
	s_lshl_b32 s101, s33, 14
	s_nop 1
	v_add_u32_e32 v82, s101, v239
	v_add_u32_e32 v102, s101, v240
	ds_read_b128 v[98:101], v82
	ds_read_b128 v[114:117], v82 offset:8192
	ds_read_b128 v[118:121], v102
	s_barrier
	s_cmp_lg_u32 s31, 2
	s_cselect_b32 s31, s26, 0
	s_cmp_lt_u32 s23, s19
	s_cbranch_scc0 .Lhd_u1o
.LBB0_214:
	s_lshl_b32 s26, s49, 14
	s_add_i32 s40, s23, 1
	s_add_i32 s54, s26, 0
	s_cmp_ge_u32 s40, s19
	v_add_u32_e32 v249, s54, v244
	v_add_u32_e32 v212, s54, v245
	s_cbranch_scc1 .Lpvo_u1o
.LBB0_225:
	s_lshl_b32 s26, s33, 14
	s_add_i32 s26, s26, 0
	s_nop 1
	ds_read_b128 v[126:129], v249 offset:49152
	s_waitcnt lgkmcnt(1)
	v_mfma_f32_32x32x16_bf16 v[82:97], v[98:101], v[146:149], v[66:81]
	ds_read_b128 v[122:125], v102 offset:8192
	v_mfma_f32_32x32x16_bf16 v[98:113], v[114:117], v[146:149], v[66:81]
	v_add_u32_e32 v139, s26, v241
	ds_read_b128 v[114:117], v139
	v_mfma_f32_32x32x16_bf16 v[82:97], v[118:121], v[150:153], v[82:97]
	ds_read_b128 v[118:121], v139 offset:8192
	s_waitcnt lgkmcnt(0)
	v_mfma_f32_32x32x16_bf16 v[98:113], v[122:125], v[150:153], v[98:113]
	v_add_u32_e32 v139, s26, v243
	ds_read_b128 v[122:125], v139
	v_mfma_f32_32x32x16_bf16 v[82:97], v[114:117], v[154:157], v[82:97]
	ds_read_b128 v[114:117], v139 offset:8192
	v_mfma_f32_32x32x16_bf16 v[98:113], v[118:121], v[154:157], v[98:113]
	s_waitcnt lgkmcnt(0)
	v_mfma_f32_32x32x16_bf16 v[82:97], v[122:125], v[158:161], v[82:97]
	v_mfma_f32_32x32x16_bf16 v[98:113], v[114:117], v[158:161], v[98:113]
	s_nop 0
	ds_read_b128 v[122:125], v249 offset:53248
	ds_read_b128 v[118:121], v249 offset:57344
	ds_read_b128 v[114:117], v249 offset:61440
	s_add_i32 s26, s21, 0x80
	s_cmp_le_u32 s26, s20
	s_cbranch_scc1 .LBB0_228
	v_add_u32_e32 v130, s21, v248
	v_add_u32_e32 v130, 0x15f, v130
	v_and_b32_e32 v130, 0x3ffffffc, v130
	v_lshl_add_u32 v162, v130, 2, v0
	ds_read_b128 v[130:133], v162
	ds_read_b128 v[134:137], v162 offset:16
	ds_read_b128 v[138:141], v162 offset:64
	ds_read_b128 v[142:145], v162 offset:80
	s_waitcnt lgkmcnt(0)
	v_pk_add_f32 v[84:85], v[84:85], v[132:133]
	v_pk_add_f32 v[86:87], v[86:87], v[134:135]
	v_pk_add_f32 v[90:91], v[90:91], v[138:139]
	v_pk_add_f32 v[94:95], v[94:95], v[142:143]
	v_pk_add_f32 v[96:97], v[96:97], v[144:145]
	v_pk_add_f32 v[92:93], v[92:93], v[140:141]
	v_pk_add_f32 v[88:89], v[88:89], v[136:137]
	v_pk_add_f32 v[82:83], v[82:83], v[130:131]
	ds_read_b128 v[130:133], v162 offset:128
	ds_read_b128 v[134:137], v162 offset:144
	ds_read_b128 v[138:141], v162 offset:192
	ds_read_b128 v[142:145], v162 offset:208
	s_waitcnt lgkmcnt(0)
	v_pk_add_f32 v[100:101], v[100:101], v[132:133]
	v_pk_add_f32 v[102:103], v[102:103], v[134:135]
	v_pk_add_f32 v[106:107], v[106:107], v[138:139]
	v_pk_add_f32 v[110:111], v[110:111], v[142:143]
	v_pk_add_f32 v[112:113], v[112:113], v[144:145]
	v_pk_add_f32 v[108:109], v[108:109], v[140:141]
	v_pk_add_f32 v[104:105], v[104:105], v[136:137]
	v_pk_add_f32 v[98:99], v[98:99], v[130:131]
.LBB0_228:
	s_waitcnt lgkmcnt(3)
	v_mfma_f32_32x32x16_bf16 v[34:49], v[126:129], v[166:169], v[34:49]
	ds_read_b128 v[126:129], v212 offset:49152
	s_nop 0
	v_exp_f32_e32 v130, v82
	v_exp_f32_e32 v131, v83
	v_add_f32_e32 v132, v1, v130
	v_add_f32_e32 v133, v1, v131
	v_cvt_pk_bf16_f32 v162, v130, v131
	s_waitcnt lgkmcnt(3)
	v_mfma_f32_32x32x16_bf16 v[50:65], v[122:125], v[166:169], v[50:65]
	ds_read_b128 v[122:125], v212 offset:53248
	v_exp_f32_e32 v130, v84
	v_exp_f32_e32 v131, v85
	s_add_i32 s23, s23, 3
	s_cmp_le_u32 s23, s16
	v_add_f32_e32 v132, v132, v130
	v_add_f32_e32 v133, v133, v131
	v_cvt_pk_bf16_f32 v163, v130, v131
	s_cselect_b64 s[26:27], -1, 0
	s_cmp_gt_u32 s23, s16
	s_cbranch_scc1 .LBB0_230
	s_lshl_b32 s23, s48, 14
	s_add_u32 s100, s8, s50
	s_addc_u32 s101, s9, s51
	s_add_i32 m0, s11, s23
	s_nop 0
	global_load_lds_dwordx4 v214, s[100:101]
.LBB0_230:
	s_waitcnt lgkmcnt(3)
	v_mfma_f32_32x32x16_bf16 v[18:33], v[118:121], v[166:169], v[18:33]
	ds_read_b128 v[118:121], v212 offset:57344
	v_exp_f32_e32 v134, v86
	v_exp_f32_e32 v135, v87
	v_add_f32_e32 v132, v132, v134
	v_add_f32_e32 v133, v133, v135
	v_cvt_pk_bf16_f32 v164, v134, v135
	s_waitcnt lgkmcnt(3)
	v_mfma_f32_32x32x16_bf16 v[2:17], v[114:117], v[166:169], v[2:17]
	ds_read_b128 v[114:117], v212 offset:61440
	v_exp_f32_e32 v134, v88
	v_exp_f32_e32 v135, v89
	v_add_f32_e32 v136, v132, v134
	v_add_f32_e32 v133, v133, v135
	v_cvt_pk_bf16_f32 v165, v134, v135
	s_waitcnt lgkmcnt(3)
	v_mfma_f32_32x32x16_bf16 v[34:49], v[126:129], v[174:177], v[34:49]
	v_add_u32_e32 v132, s54, v246
	ds_read_b128 v[126:129], v132 offset:49152
	v_exp_f32_e32 v134, v90
	v_exp_f32_e32 v135, v91
	v_add_f32_e32 v136, v136, v134
	v_add_f32_e32 v137, v133, v135
	v_cvt_pk_bf16_f32 v170, v134, v135
	s_waitcnt lgkmcnt(3)
	v_mfma_f32_32x32x16_bf16 v[50:65], v[122:125], v[174:177], v[50:65]
	ds_read_b128 v[122:125], v132 offset:53248
	v_exp_f32_e32 v135, v92
	v_exp_f32_e32 v138, v93
	v_add_f32_e32 v133, v136, v135
	v_add_f32_e32 v134, v137, v138
	s_andn2_b64 vcc, exec, s[26:27]
	v_cvt_pk_bf16_f32 v171, v135, v138
	s_cbranch_vccnz .LBB0_232
	s_lshl_b32 s23, s48, 14
	s_add_i32 s23, s11, s23
	s_add_u32 s100, s8, s4
	s_addc_u32 s101, s9, s5
	s_add_i32 m0, s23, 0x2000
	s_nop 0
	global_load_lds_dwordx4 v214, s[100:101]
.LBB0_232:
	s_waitcnt lgkmcnt(3)
	v_mfma_f32_32x32x16_bf16 v[18:33], v[118:121], v[174:177], v[18:33]
	ds_read_b128 v[118:121], v132 offset:57344
	v_exp_f32_e32 v130, v94
	v_exp_f32_e32 v131, v95
	v_add_f32_e32 v133, v133, v130
	v_add_f32_e32 v134, v134, v131
	v_cvt_pk_bf16_f32 v172, v130, v131
	s_waitcnt lgkmcnt(3)
	v_mfma_f32_32x32x16_bf16 v[2:17], v[114:117], v[174:177], v[2:17]
	ds_read_b128 v[114:117], v132 offset:61440
	v_exp_f32_e32 v130, v96
	v_exp_f32_e32 v131, v97
	v_add_f32_e32 v133, v133, v130
	v_add_f32_e32 v134, v134, v131
	v_cvt_pk_bf16_f32 v173, v130, v131
	s_waitcnt lgkmcnt(3)
	v_mfma_f32_32x32x16_bf16 v[34:49], v[126:129], v[182:185], v[34:49]
	v_add_u32_e32 v132, s54, v247
	ds_read_b128 v[126:129], v132 offset:49152
	v_exp_f32_e32 v130, v98
	v_exp_f32_e32 v131, v99
	v_add_f32_e32 v133, v133, v130
	v_add_f32_e32 v134, v134, v131
	v_cvt_pk_bf16_f32 v178, v130, v131
	s_waitcnt lgkmcnt(3)
	v_mfma_f32_32x32x16_bf16 v[50:65], v[122:125], v[182:185], v[50:65]
	v_exp_f32_e32 v130, v100
	v_exp_f32_e32 v131, v101
	ds_read_b128 v[122:125], v132 offset:53248
	v_add_f32_e32 v133, v133, v130
	v_add_f32_e32 v134, v134, v131
	v_cvt_pk_bf16_f32 v179, v130, v131
	s_cmp_eq_u64 s[88:89], 0
	s_cbranch_scc1 .LBB0_234
	s_lshl_b32 s23, s31, 14
	s_add_i32 s23, s11, s23
	s_add_i32 m0, s23, 0xc000
	s_add_u32 s100, s8, s0
	s_addc_u32 s101, s9, s1
	global_load_lds_dwordx4 v216, s[100:101]
.LBB0_234:
	s_waitcnt lgkmcnt(3)
	v_mfma_f32_32x32x16_bf16 v[18:33], v[118:121], v[182:185], v[18:33]
	ds_read_b128 v[118:121], v132 offset:57344
	v_exp_f32_e32 v135, v102
	v_exp_f32_e32 v136, v103
	v_add_f32_e32 v133, v133, v135
	v_add_f32_e32 v134, v134, v136
	v_cvt_pk_bf16_f32 v180, v135, v136
	s_waitcnt lgkmcnt(3)
	v_mfma_f32_32x32x16_bf16 v[2:17], v[114:117], v[182:185], v[2:17]
	ds_read_b128 v[114:117], v132 offset:61440
	v_exp_f32_e32 v132, v104
	v_exp_f32_e32 v135, v105
	v_add_f32_e32 v133, v133, v132
	v_add_f32_e32 v134, v134, v135
	v_cvt_pk_bf16_f32 v181, v132, v135
	s_waitcnt lgkmcnt(3)
	v_mfma_f32_32x32x16_bf16 v[34:49], v[126:129], v[190:193], v[34:49]
	v_exp_f32_e32 v126, v106
	v_exp_f32_e32 v127, v107
	v_add_f32_e32 v128, v133, v126
	v_add_f32_e32 v129, v134, v127
	v_cvt_pk_bf16_f32 v186, v126, v127
	s_waitcnt lgkmcnt(2)
	v_mfma_f32_32x32x16_bf16 v[50:65], v[122:125], v[190:193], v[50:65]
	v_exp_f32_e32 v124, v108
	v_exp_f32_e32 v125, v109
	v_add_f32_e32 v122, v128, v124
	v_add_f32_e32 v123, v129, v125
	s_cmp_eq_u64 s[88:89], 0
	v_cvt_pk_bf16_f32 v187, v124, v125
	s_cbranch_scc1 .LBB0_236
	s_lshl_b32 s23, s31, 14
	s_add_i32 s23, s11, s23
	s_add_u32 s100, s8, s52
	s_addc_u32 s101, s9, s53
	s_add_i32 m0, s23, 0xe000
	s_nop 0
	global_load_lds_dwordx4 v216, s[100:101]
.LBB0_236:
	s_waitcnt lgkmcnt(1)
	v_mfma_f32_32x32x16_bf16 v[18:33], v[118:121], v[190:193], v[18:33]
	v_exp_f32_e32 v118, v110
	v_exp_f32_e32 v119, v111
	v_add_f32_e32 v120, v122, v118
	v_add_f32_e32 v121, v123, v119
	v_cvt_pk_bf16_f32 v188, v118, v119
	s_waitcnt lgkmcnt(0)
	v_mfma_f32_32x32x16_bf16 v[2:17], v[114:117], v[190:193], v[2:17]
	v_exp_f32_e32 v114, v112
	v_exp_f32_e32 v115, v113
	v_add_f32_e32 v116, v120, v114
	v_add_f32_e32 v117, v121, v115
	v_cvt_pk_bf16_f32 v189, v114, v115
	v_add_f32_e32 v212, v116, v117
	v_cmp_nge_f32_e32 vcc, s7, v212
	s_cbranch_vccnz .Lrare_u1o
.LBB0_238:
	v_add_f32_e32 v242, v212, v242
.LBB0_240:
	s_add_i32 s23, s33, 1
	s_cmp_lg_u32 s33, 2
	s_cselect_b32 s33, s23, 0
	s_add_i32 s23, s48, 1
	s_cmp_lg_u32 s48, 2
	s_cselect_b32 s48, s23, 0
	s_add_i32 s23, s49, 1
	s_cmp_lg_u32 s49, 2
	s_cselect_b32 s49, s23, 0
	s_add_i32 s23, s31, 1
	s_cmp_lg_u32 s31, 2
	s_cselect_b32 s31, s23, 0
	s_addk_i32 s21, 0x80
	s_add_i32 s23, s22, -3
	v_lshl_add_u64 v[214:215], v[214:215], 0, s[34:35]
	s_cmp_ge_u32 s23, s16
	v_lshl_add_u64 v[216:217], v[216:217], 0, s[24:25]
	s_cbranch_scc1 .LBB0_242
	s_mov_b32 s23, s22
	s_branch .LBB0_164
.Lrare_u1e:
	v_max_f32_e32 v66, v99, v99
	v_max_f32_e32 v67, v83, v83
	v_max_f32_e32 v66, v67, v66
	v_max3_f32 v66, v82, v98, v66
	v_max3_f32 v67, v100, v85, v101
	v_max3_f32 v66, v66, v84, v67
	v_max3_f32 v67, v102, v87, v103
	v_max3_f32 v66, v66, v86, v67
	v_max3_f32 v67, v104, v89, v105
	v_max3_f32 v66, v66, v88, v67
	v_max3_f32 v67, v106, v91, v107
	v_max3_f32 v66, v66, v90, v67
	v_max3_f32 v67, v108, v93, v109
	v_max3_f32 v66, v66, v92, v67
	v_max3_f32 v67, v110, v95, v111
	v_max3_f32 v66, v66, v94, v67
	v_max3_f32 v67, v112, v97, v113
	v_max3_f32 v66, v66, v96, v67
	v_mov_b32_e32 v67, v66
	s_nop 1
	v_permlane32_swap_b32_e32 v66, v67
	v_max_f32_e32 v67, v67, v67
	v_max_f32_e32 v66, v66, v66
	v_max_f32_e32 v66, v66, v67
	v_cmp_lt_f32_e32 vcc, s57, v66
	s_nop 1
	v_cndmask_b32_e32 v68, 0, v66, vcc
	v_sub_f32_e32 v66, v82, v68
	v_exp_f32_e32 v116, v66
	v_sub_f32_e32 v66, v98, v68
	v_exp_f32_e32 v117, v66
	v_sub_f32_e32 v66, v83, v68
	v_exp_f32_e32 v118, v66
	v_sub_f32_e32 v66, v99, v68
	v_exp_f32_e32 v119, v66
	v_sub_f32_e32 v66, v84, v68
	v_exp_f32_e32 v98, v66
	v_sub_f32_e32 v66, v100, v68
	v_exp_f32_e32 v82, v66
	v_add_f32_e32 v66, v117, v116
	v_add_f32_e32 v99, 0, v66
	v_add_f32_e32 v83, v119, v118
	v_pk_add_f32 v[66:67], v[82:83], v[98:99]
	v_cvt_pk_bf16_f32 v166, v116, v118
	v_pk_add_f32 v[114:115], v[66:67], v[66:67] op_sel_hi:[0,1]
	v_sub_f32_e32 v66, v85, v68
	v_exp_f32_e32 v83, v66
	v_sub_f32_e32 v66, v101, v68
	v_exp_f32_e32 v99, v66
	v_sub_f32_e32 v66, v86, v68
	v_exp_f32_e32 v114, v66
	v_sub_f32_e32 v66, v102, v68
	v_exp_f32_e32 v84, v66
	v_add_f32_e32 v85, v99, v83
	v_cvt_pk_bf16_f32 v167, v98, v83
	v_cvt_pk_bf16_f32 v182, v117, v119
	v_pk_add_f32 v[66:67], v[84:85], v[114:115]
	v_cvt_pk_bf16_f32 v183, v82, v99
	v_pk_add_f32 v[100:101], v[66:67], v[66:67] op_sel_hi:[0,1]
	v_sub_f32_e32 v66, v87, v68
	v_exp_f32_e32 v85, v66
	v_sub_f32_e32 v66, v103, v68
	v_exp_f32_e32 v115, v66
	v_sub_f32_e32 v66, v88, v68
	v_exp_f32_e32 v100, v66
	v_sub_f32_e32 v66, v104, v68
	v_exp_f32_e32 v86, v66
	v_add_f32_e32 v87, v115, v85
	v_cvt_pk_bf16_f32 v168, v114, v85
	v_cvt_pk_bf16_f32 v184, v84, v115
	v_pk_add_f32 v[66:67], v[86:87], v[100:101]
	s_nop 0
	v_pk_add_f32 v[102:103], v[66:67], v[66:67] op_sel_hi:[0,1]
	v_sub_f32_e32 v66, v89, v68
	v_exp_f32_e32 v87, v66
	v_sub_f32_e32 v66, v105, v68
	v_exp_f32_e32 v101, v66
	v_sub_f32_e32 v66, v90, v68
	v_exp_f32_e32 v102, v66
	v_sub_f32_e32 v66, v106, v68
	v_exp_f32_e32 v88, v66
	v_add_f32_e32 v89, v101, v87
	v_cvt_pk_bf16_f32 v169, v100, v87
	v_cvt_pk_bf16_f32 v185, v86, v101
	v_pk_add_f32 v[66:67], v[88:89], v[102:103]
	s_nop 0
	v_pk_add_f32 v[104:105], v[66:67], v[66:67] op_sel_hi:[0,1]
	v_sub_f32_e32 v66, v91, v68
	v_exp_f32_e32 v89, v66
	v_sub_f32_e32 v66, v107, v68
	v_exp_f32_e32 v103, v66
	v_sub_f32_e32 v66, v92, v68
	v_exp_f32_e32 v104, v66
	v_sub_f32_e32 v66, v108, v68
	v_exp_f32_e32 v90, v66
	v_sub_f32_e32 v66, v97, v68
	v_add_f32_e32 v91, v103, v89
	v_exp_f32_e32 v97, v66
	v_pk_add_f32 v[66:67], v[90:91], v[104:105]
	v_cvt_pk_bf16_f32 v174, v102, v89
	v_pk_add_f32 v[106:107], v[66:67], v[66:67] op_sel_hi:[0,1]
	v_sub_f32_e32 v66, v93, v68
	v_exp_f32_e32 v91, v66
	v_sub_f32_e32 v66, v109, v68
	v_exp_f32_e32 v105, v66
	v_sub_f32_e32 v66, v94, v68
	v_exp_f32_e32 v106, v66
	v_sub_f32_e32 v66, v110, v68
	v_exp_f32_e32 v92, v66
	v_sub_f32_e32 v66, v113, v68
	v_add_f32_e32 v93, v105, v91
	v_exp_f32_e32 v110, v66
	v_pk_add_f32 v[66:67], v[92:93], v[106:107]
	v_cvt_pk_bf16_f32 v175, v104, v91
	v_pk_add_f32 v[108:109], v[66:67], v[66:67] op_sel_hi:[0,1]
	v_sub_f32_e32 v66, v95, v68
	v_exp_f32_e32 v93, v66
	v_sub_f32_e32 v66, v111, v68
	v_exp_f32_e32 v107, v66
	v_sub_f32_e32 v66, v96, v68
	v_exp_f32_e32 v108, v66
	v_sub_f32_e32 v66, v112, v68
	v_exp_f32_e32 v94, v66
	v_add_f32_e32 v95, v107, v93
	v_exp_f32_e64 v96, -v68
	v_add_f32_e32 v212, v110, v97
	v_pk_add_f32 v[66:67], v[94:95], v[108:109]
	v_cvt_pk_bf16_f32 v176, v106, v93
	v_pk_add_f32 v[66:67], v[66:67], v[66:67] op_sel:[0,1] op_sel_hi:[1,0]
	v_pk_mul_f32 v[48:49], v[48:49], v[96:97] op_sel_hi:[1,0]
	v_mov_b32_e32 v67, v68
	v_pk_add_f32 v[212:213], v[212:213], v[66:67]
	v_pk_mul_f32 v[46:47], v[46:47], v[96:97] op_sel_hi:[1,0]
	v_xor_b32_e32 v66, 0x80000000, v213
	v_mov_b32_e32 v67, v66
	v_mov_b32_e32 v68, v66
	v_mov_b32_e32 v69, v66
	v_mov_b32_e32 v70, v66
	v_mov_b32_e32 v71, v66
	v_mov_b32_e32 v72, v66
	v_mov_b32_e32 v73, v66
	v_mov_b32_e32 v74, v66
	v_mov_b32_e32 v75, v66
	v_mov_b32_e32 v76, v66
	v_mov_b32_e32 v77, v66
	v_mov_b32_e32 v78, v66
	v_mov_b32_e32 v79, v66
	v_mov_b32_e32 v80, v66
	v_mov_b32_e32 v81, v66
	v_pk_mul_f32 v[44:45], v[44:45], v[96:97] op_sel_hi:[1,0]
	v_pk_mul_f32 v[42:43], v[42:43], v[96:97] op_sel_hi:[1,0]
	v_pk_mul_f32 v[40:41], v[40:41], v[96:97] op_sel_hi:[1,0]
	v_pk_mul_f32 v[38:39], v[38:39], v[96:97] op_sel_hi:[1,0]
	v_pk_mul_f32 v[36:37], v[36:37], v[96:97] op_sel_hi:[1,0]
	v_pk_mul_f32 v[34:35], v[34:35], v[96:97] op_sel_hi:[1,0]
	v_pk_mul_f32 v[64:65], v[64:65], v[96:97] op_sel_hi:[1,0]
	v_pk_mul_f32 v[62:63], v[62:63], v[96:97] op_sel_hi:[1,0]
	v_pk_mul_f32 v[60:61], v[60:61], v[96:97] op_sel_hi:[1,0]
	v_pk_mul_f32 v[58:59], v[58:59], v[96:97] op_sel_hi:[1,0]
	v_pk_mul_f32 v[56:57], v[56:57], v[96:97] op_sel_hi:[1,0]
	v_pk_mul_f32 v[54:55], v[54:55], v[96:97] op_sel_hi:[1,0]
	v_pk_mul_f32 v[52:53], v[52:53], v[96:97] op_sel_hi:[1,0]
	v_pk_mul_f32 v[50:51], v[50:51], v[96:97] op_sel_hi:[1,0]
	v_pk_mul_f32 v[32:33], v[32:33], v[96:97] op_sel_hi:[1,0]
	v_pk_mul_f32 v[30:31], v[30:31], v[96:97] op_sel_hi:[1,0]
	v_pk_mul_f32 v[28:29], v[28:29], v[96:97] op_sel_hi:[1,0]
	v_pk_mul_f32 v[26:27], v[26:27], v[96:97] op_sel_hi:[1,0]
	v_pk_mul_f32 v[24:25], v[24:25], v[96:97] op_sel_hi:[1,0]
	v_pk_mul_f32 v[22:23], v[22:23], v[96:97] op_sel_hi:[1,0]
	v_pk_mul_f32 v[20:21], v[20:21], v[96:97] op_sel_hi:[1,0]
	v_pk_mul_f32 v[18:19], v[18:19], v[96:97] op_sel_hi:[1,0]
	v_pk_mul_f32 v[16:17], v[16:17], v[96:97] op_sel_hi:[1,0]
	v_pk_mul_f32 v[14:15], v[14:15], v[96:97] op_sel_hi:[1,0]
	v_pk_mul_f32 v[12:13], v[12:13], v[96:97] op_sel_hi:[1,0]
	v_pk_mul_f32 v[10:11], v[10:11], v[96:97] op_sel_hi:[1,0]
	v_pk_mul_f32 v[8:9], v[8:9], v[96:97] op_sel_hi:[1,0]
	v_pk_mul_f32 v[6:7], v[6:7], v[96:97] op_sel_hi:[1,0]
	v_pk_mul_f32 v[4:5], v[4:5], v[96:97] op_sel_hi:[1,0]
	v_pk_mul_f32 v[2:3], v[2:3], v[96:97] op_sel_hi:[1,0]
	v_mul_f32_e32 v242, v242, v96
	v_cvt_pk_bf16_f32 v177, v108, v97
	v_cvt_pk_bf16_f32 v190, v88, v103
	v_cvt_pk_bf16_f32 v191, v90, v105
	v_cvt_pk_bf16_f32 v192, v92, v107
	v_cvt_pk_bf16_f32 v193, v94, v110
	s_branch .LBB0_198
.LBB0_199:
	s_nop 3
	v_mov_b64_e32 v[34:35], v[82:83]
	v_mov_b64_e32 v[50:51], v[98:99]
	s_nop 1
	v_mov_b64_e32 v[18:19], v[114:115]
	v_mov_b64_e32 v[2:3], v[130:131]
	v_mov_b64_e32 v[36:37], v[84:85]
	v_mov_b64_e32 v[38:39], v[86:87]
	v_mov_b64_e32 v[40:41], v[88:89]
	v_mov_b64_e32 v[42:43], v[90:91]
	v_mov_b64_e32 v[44:45], v[92:93]
	v_mov_b64_e32 v[46:47], v[94:95]
	v_mov_b64_e32 v[48:49], v[96:97]
	v_mov_b64_e32 v[52:53], v[100:101]
	v_mov_b64_e32 v[54:55], v[102:103]
	v_mov_b64_e32 v[56:57], v[104:105]
	v_mov_b64_e32 v[58:59], v[106:107]
	v_mov_b64_e32 v[60:61], v[108:109]
	v_mov_b64_e32 v[62:63], v[110:111]
	v_mov_b64_e32 v[64:65], v[112:113]
	v_mov_b64_e32 v[20:21], v[116:117]
	v_mov_b64_e32 v[22:23], v[118:119]
	v_mov_b64_e32 v[24:25], v[120:121]
	v_mov_b64_e32 v[26:27], v[122:123]
	v_mov_b64_e32 v[28:29], v[124:125]
	v_mov_b64_e32 v[30:31], v[126:127]
	v_mov_b64_e32 v[32:33], v[128:129]
	v_mov_b64_e32 v[4:5], v[132:133]
	v_mov_b64_e32 v[6:7], v[134:135]
	v_mov_b64_e32 v[8:9], v[136:137]
	v_mov_b64_e32 v[10:11], v[138:139]
	v_mov_b64_e32 v[12:13], v[140:141]
	v_mov_b64_e32 v[14:15], v[142:143]
	v_mov_b64_e32 v[16:17], v[144:145]
	s_branch .LBB0_200
.Lhd_u1e:
	s_add_i32 s22, s23, 2
	s_cmp_ge_u32 s22, s17
	s_cbranch_scc1 .LBB0_171
	s_lshl_b32 s26, s48, 14
	s_add_i32 s26, s11, s26
	s_add_i32 s27, s26, 0x2000
	s_mov_b32 m0, s26
	s_add_u32 s100, s8, s80
	s_addc_u32 s101, s9, s81
	global_load_lds_dwordx4 v214, s[100:101]
	s_mov_b32 m0, s27
	s_add_u32 s100, s8, s62
	s_addc_u32 s101, s9, s63
	global_load_lds_dwordx4 v214, s[100:101]

.LBB0_173:
	s_mov_b64 s[26:27], 0
	s_branch .LBB0_200
.Lpvo_u1e:
	s_mov_b64 s[26:27], -1
	ds_read_b128 v[98:101], v249 offset:49152
	ds_read_b128 v[114:117], v249 offset:53248
	ds_read_b128 v[130:133], v249 offset:57344
	ds_read_b128 v[194:197], v249 offset:61440
	s_waitcnt lgkmcnt(0)
	v_mfma_f32_32x32x16_bf16 v[82:97], v[98:101], v[162:165], v[34:49]
	ds_read_b128 v[206:209], v212 offset:49152
	v_mfma_f32_32x32x16_bf16 v[98:113], v[114:117], v[162:165], v[50:65]
	ds_read_b128 v[198:201], v212 offset:53248
	s_add_i32 s22, s23, 2
	s_cmp_lt_u32 s22, s17
	s_cselect_b64 s[26:27], -1, 0
	s_cmp_ge_u32 s22, s17
	s_cbranch_scc1 .LBB0_178
	s_lshl_b32 s40, s48, 14
	s_add_i32 m0, s11, s40
	s_add_u32 s100, s8, s80
	s_addc_u32 s101, s9, s81
	global_load_lds_dwordx4 v214, s[100:101]

.LBB0_184:
	v_mfma_f32_32x32x16_bf16 v[114:129], v[202:205], v[186:189], v[114:129]
	v_mfma_f32_32x32x16_bf16 v[130:145], v[194:197], v[186:189], v[130:145]
	s_mov_b64 s[26:27], 0
	s_branch .LBB0_199
.Lrare_u1o:
	v_max_f32_e32 v66, v99, v99
	v_max_f32_e32 v67, v83, v83
	v_max_f32_e32 v66, v67, v66
	v_max3_f32 v66, v82, v98, v66
	v_max3_f32 v67, v100, v85, v101
	v_max3_f32 v66, v66, v84, v67
	v_max3_f32 v67, v102, v87, v103
	v_max3_f32 v66, v66, v86, v67
	v_max3_f32 v67, v104, v89, v105
	v_max3_f32 v66, v66, v88, v67
	v_max3_f32 v67, v106, v91, v107
	v_max3_f32 v66, v66, v90, v67
	v_max3_f32 v67, v108, v93, v109
	v_max3_f32 v66, v66, v92, v67
	v_max3_f32 v67, v110, v95, v111
	v_max3_f32 v66, v66, v94, v67
	v_max3_f32 v67, v112, v97, v113
	v_max3_f32 v66, v66, v96, v67
	v_mov_b32_e32 v67, v66
	s_nop 1
	v_permlane32_swap_b32_e32 v66, v67
	v_max_f32_e32 v67, v67, v67
	v_max_f32_e32 v66, v66, v66
	v_max_f32_e32 v66, v66, v67
	v_cmp_lt_f32_e32 vcc, s57, v66
	s_nop 1
	v_cndmask_b32_e32 v68, 0, v66, vcc
	v_sub_f32_e32 v66, v82, v68
	v_exp_f32_e32 v116, v66
	v_sub_f32_e32 v66, v98, v68
	v_exp_f32_e32 v117, v66
	v_sub_f32_e32 v66, v83, v68
	v_exp_f32_e32 v118, v66
	v_sub_f32_e32 v66, v99, v68
	v_exp_f32_e32 v119, v66
	v_sub_f32_e32 v66, v84, v68
	v_exp_f32_e32 v114, v66
	v_sub_f32_e32 v66, v100, v68
	v_exp_f32_e32 v82, v66
	v_add_f32_e32 v66, v116, v117
	v_add_f32_e32 v83, 0, v66
	v_add_f32_e32 v115, v118, v119
	v_pk_add_f32 v[66:67], v[114:115], v[82:83]
	v_cvt_pk_bf16_f32 v162, v116, v118
	v_pk_add_f32 v[98:99], v[66:67], v[66:67] op_sel_hi:[0,1]
	v_sub_f32_e32 v66, v85, v68
	v_exp_f32_e32 v83, v66
	v_sub_f32_e32 v66, v101, v68
	v_exp_f32_e32 v115, v66
	v_sub_f32_e32 v66, v86, v68
	v_exp_f32_e32 v100, v66
	v_sub_f32_e32 v66, v102, v68
	v_exp_f32_e32 v98, v66
	v_add_f32_e32 v101, v83, v115
	v_cvt_pk_bf16_f32 v163, v114, v83
	v_cvt_pk_bf16_f32 v178, v117, v119
	v_pk_add_f32 v[66:67], v[100:101], v[98:99]
	v_cvt_pk_bf16_f32 v179, v82, v115
	v_pk_add_f32 v[84:85], v[66:67], v[66:67] op_sel_hi:[0,1]
	v_sub_f32_e32 v66, v87, v68
	v_exp_f32_e32 v99, v66
	v_sub_f32_e32 v66, v103, v68
	v_exp_f32_e32 v101, v66
	v_sub_f32_e32 v66, v88, v68
	v_exp_f32_e32 v102, v66
	v_sub_f32_e32 v66, v104, v68
	v_exp_f32_e32 v84, v66
	v_add_f32_e32 v103, v99, v101
	v_cvt_pk_bf16_f32 v164, v100, v99
	v_cvt_pk_bf16_f32 v180, v98, v101
	v_pk_add_f32 v[66:67], v[102:103], v[84:85]
	s_nop 0
	v_pk_add_f32 v[86:87], v[66:67], v[66:67] op_sel_hi:[0,1]
	v_sub_f32_e32 v66, v89, v68
	v_exp_f32_e32 v85, v66
	v_sub_f32_e32 v66, v105, v68
	v_exp_f32_e32 v103, v66
	v_sub_f32_e32 v66, v90, v68
	v_exp_f32_e32 v104, v66
	v_sub_f32_e32 v66, v106, v68
	v_exp_f32_e32 v86, v66
	v_add_f32_e32 v105, v85, v103
	v_cvt_pk_bf16_f32 v165, v102, v85
	v_cvt_pk_bf16_f32 v181, v84, v103
	v_pk_add_f32 v[66:67], v[104:105], v[86:87]
	s_nop 0
	v_pk_add_f32 v[88:89], v[66:67], v[66:67] op_sel_hi:[0,1]
	v_sub_f32_e32 v66, v91, v68
	v_exp_f32_e32 v87, v66
	v_sub_f32_e32 v66, v107, v68
	v_exp_f32_e32 v105, v66
	v_sub_f32_e32 v66, v92, v68
	v_exp_f32_e32 v90, v66
	v_sub_f32_e32 v66, v108, v68
	v_exp_f32_e32 v88, v66
	v_sub_f32_e32 v66, v97, v68
	v_add_f32_e32 v91, v87, v105
	v_exp_f32_e32 v97, v66
	v_pk_add_f32 v[66:67], v[90:91], v[88:89]
	v_cvt_pk_bf16_f32 v170, v104, v87
	v_pk_add_f32 v[106:107], v[66:67], v[66:67] op_sel_hi:[0,1]
	v_sub_f32_e32 v66, v93, v68
	v_exp_f32_e32 v89, v66
	v_sub_f32_e32 v66, v109, v68
	v_exp_f32_e32 v91, v66
	v_sub_f32_e32 v66, v94, v68
	v_exp_f32_e32 v92, v66
	v_sub_f32_e32 v66, v110, v68
	v_exp_f32_e32 v106, v66
	v_sub_f32_e32 v66, v113, v68
	v_add_f32_e32 v93, v89, v91
	v_exp_f32_e32 v110, v66
	v_pk_add_f32 v[66:67], v[92:93], v[106:107]
	v_cvt_pk_bf16_f32 v171, v90, v89
	v_pk_add_f32 v[108:109], v[66:67], v[66:67] op_sel_hi:[0,1]
	v_sub_f32_e32 v66, v95, v68
	v_exp_f32_e32 v93, v66
	v_sub_f32_e32 v66, v111, v68
	v_exp_f32_e32 v107, v66
	v_sub_f32_e32 v66, v96, v68
	v_exp_f32_e32 v94, v66
	v_sub_f32_e32 v66, v112, v68
	v_exp_f32_e32 v108, v66
	v_add_f32_e32 v95, v93, v107
	v_exp_f32_e64 v96, -v68
	v_add_f32_e32 v212, v97, v110
	v_pk_add_f32 v[66:67], v[94:95], v[108:109]
	v_cvt_pk_bf16_f32 v172, v92, v93
	v_pk_add_f32 v[66:67], v[66:67], v[66:67] op_sel:[0,1] op_sel_hi:[1,0]
	v_pk_mul_f32 v[48:49], v[48:49], v[96:97] op_sel_hi:[1,0]
	v_mov_b32_e32 v67, v68
	v_pk_add_f32 v[212:213], v[212:213], v[66:67]
	v_pk_mul_f32 v[46:47], v[46:47], v[96:97] op_sel_hi:[1,0]
	v_xor_b32_e32 v66, 0x80000000, v213
	v_mov_b32_e32 v67, v66
	v_mov_b32_e32 v68, v66
	v_mov_b32_e32 v69, v66
	v_mov_b32_e32 v70, v66
	v_mov_b32_e32 v71, v66
	v_mov_b32_e32 v72, v66
	v_mov_b32_e32 v73, v66
	v_mov_b32_e32 v74, v66
	v_mov_b32_e32 v75, v66
	v_mov_b32_e32 v76, v66
	v_mov_b32_e32 v77, v66
	v_mov_b32_e32 v78, v66
	v_mov_b32_e32 v79, v66
	v_mov_b32_e32 v80, v66
	v_mov_b32_e32 v81, v66
	v_pk_mul_f32 v[44:45], v[44:45], v[96:97] op_sel_hi:[1,0]
	v_pk_mul_f32 v[42:43], v[42:43], v[96:97] op_sel_hi:[1,0]
	v_pk_mul_f32 v[40:41], v[40:41], v[96:97] op_sel_hi:[1,0]
	v_pk_mul_f32 v[38:39], v[38:39], v[96:97] op_sel_hi:[1,0]
	v_pk_mul_f32 v[36:37], v[36:37], v[96:97] op_sel_hi:[1,0]
	v_pk_mul_f32 v[34:35], v[34:35], v[96:97] op_sel_hi:[1,0]
	v_pk_mul_f32 v[64:65], v[64:65], v[96:97] op_sel_hi:[1,0]
	v_pk_mul_f32 v[62:63], v[62:63], v[96:97] op_sel_hi:[1,0]
	v_pk_mul_f32 v[60:61], v[60:61], v[96:97] op_sel_hi:[1,0]
	v_pk_mul_f32 v[58:59], v[58:59], v[96:97] op_sel_hi:[1,0]
	v_pk_mul_f32 v[56:57], v[56:57], v[96:97] op_sel_hi:[1,0]
	v_pk_mul_f32 v[54:55], v[54:55], v[96:97] op_sel_hi:[1,0]
	v_pk_mul_f32 v[52:53], v[52:53], v[96:97] op_sel_hi:[1,0]
	v_pk_mul_f32 v[50:51], v[50:51], v[96:97] op_sel_hi:[1,0]
	v_pk_mul_f32 v[32:33], v[32:33], v[96:97] op_sel_hi:[1,0]
	v_pk_mul_f32 v[30:31], v[30:31], v[96:97] op_sel_hi:[1,0]
	v_pk_mul_f32 v[28:29], v[28:29], v[96:97] op_sel_hi:[1,0]
	v_pk_mul_f32 v[26:27], v[26:27], v[96:97] op_sel_hi:[1,0]
	v_pk_mul_f32 v[24:25], v[24:25], v[96:97] op_sel_hi:[1,0]
	v_pk_mul_f32 v[22:23], v[22:23], v[96:97] op_sel_hi:[1,0]
	v_pk_mul_f32 v[20:21], v[20:21], v[96:97] op_sel_hi:[1,0]
	v_pk_mul_f32 v[18:19], v[18:19], v[96:97] op_sel_hi:[1,0]
	v_pk_mul_f32 v[16:17], v[16:17], v[96:97] op_sel_hi:[1,0]
	v_pk_mul_f32 v[14:15], v[14:15], v[96:97] op_sel_hi:[1,0]
	v_pk_mul_f32 v[12:13], v[12:13], v[96:97] op_sel_hi:[1,0]
	v_pk_mul_f32 v[10:11], v[10:11], v[96:97] op_sel_hi:[1,0]
	v_pk_mul_f32 v[8:9], v[8:9], v[96:97] op_sel_hi:[1,0]
	v_pk_mul_f32 v[6:7], v[6:7], v[96:97] op_sel_hi:[1,0]
	v_pk_mul_f32 v[4:5], v[4:5], v[96:97] op_sel_hi:[1,0]
	v_pk_mul_f32 v[2:3], v[2:3], v[96:97] op_sel_hi:[1,0]
	v_mul_f32_e32 v242, v242, v96
	v_cvt_pk_bf16_f32 v173, v94, v97
	v_cvt_pk_bf16_f32 v186, v86, v105
	v_cvt_pk_bf16_f32 v187, v88, v91
	v_cvt_pk_bf16_f32 v188, v106, v107
	v_cvt_pk_bf16_f32 v189, v108, v110
	s_branch .LBB0_238

.Lhd_u1o:
	s_add_i32 s26, s23, 3
	s_cmp_gt_u32 s26, s16
	s_cbranch_scc1 .LBB0_211
	s_lshl_b32 s26, s48, 14
	s_add_i32 s26, s11, s26
	s_add_i32 s27, s26, 0x2000
	s_mov_b32 m0, s26
	s_add_u32 s100, s8, s50
	s_addc_u32 s101, s9, s51
	global_load_lds_dwordx4 v214, s[100:101]
	s_mov_b32 m0, s27
	s_add_u32 s100, s8, s4
	s_addc_u32 s101, s9, s5
	global_load_lds_dwordx4 v214, s[100:101]

.Lpvo_u1o:
	s_mov_b64 s[26:27], -1
	ds_read_b128 v[98:101], v249 offset:49152
	ds_read_b128 v[114:117], v249 offset:53248
	ds_read_b128 v[130:133], v249 offset:57344
	ds_read_b128 v[194:197], v249 offset:61440
	s_waitcnt lgkmcnt(0)
	v_mfma_f32_32x32x16_bf16 v[82:97], v[98:101], v[166:169], v[34:49]
	ds_read_b128 v[206:209], v212 offset:49152
	v_mfma_f32_32x32x16_bf16 v[98:113], v[114:117], v[166:169], v[50:65]
	ds_read_b128 v[198:201], v212 offset:53248
	s_add_i32 s40, s23, 3
	s_cmp_le_u32 s40, s16
	s_cselect_b64 s[26:27], -1, 0
	s_cmp_gt_u32 s40, s16
	s_cbranch_scc1 .LBB0_218
	s_lshl_b32 s40, s48, 14
	s_add_i32 m0, s11, s40
	s_add_u32 s100, s8, s50
	s_addc_u32 s101, s9, s51
	global_load_lds_dwordx4 v214, s[100:101]

.LBB0_224:
	v_mfma_f32_32x32x16_bf16 v[114:129], v[202:205], v[190:193], v[114:129]
	v_mfma_f32_32x32x16_bf16 v[130:145], v[194:197], v[190:193], v[130:145]
	s_mov_b64 s[26:27], 0
	s_branch .LBB0_239
.Lotail_u1o:
	s_cmp_eq_u64 s[86:87], 0
	s_cbranch_scc1 .Low2_u1o
	s_waitcnt vmcnt(0)
	s_branch .LBB0_208

.LBB0_267:
	s_add_i32 s21, s22, -1
	s_cmp_lt_u32 s21, s17
	s_cselect_b64 s[44:45], -1, 0
	s_cmp_ge_u32 s21, s17
	s_cselect_b64 s[38:39], -1, 0
	s_waitcnt vmcnt(2)
.LBB0_271:
	s_lshl_b32 s101, s31, 14
	s_nop 1
	v_add_u32_e32 v82, s101, v239
	v_add_u32_e32 v102, s101, v240
	ds_read_b128 v[98:101], v82
	ds_read_b128 v[114:117], v82 offset:8192
	ds_read_b128 v[118:121], v102
	s_barrier
	s_cmp_lt_u32 s21, s19
	s_cbranch_scc0 .Lhd_u2e
.LBB0_277:
	s_lshl_b32 s21, s33, 14
	s_add_i32 s36, s21, 0
	s_cmp_ge_u32 s22, s19
	v_add_u32_e32 v212, s36, v245
	v_add_u32_e32 v0, s36, v246
	s_cbranch_scc1 .Lpvo_u2e
.LBB0_288:
	s_lshl_b32 s21, s31, 14
	s_add_i32 s21, s21, 0
	s_nop 1
	ds_read_b128 v[126:129], v212 offset:49152
	s_waitcnt lgkmcnt(1)
	v_mfma_f32_32x32x16_bf16 v[82:97], v[98:101], v[146:149], v[66:81]
	ds_read_b128 v[122:125], v102 offset:8192
	v_mfma_f32_32x32x16_bf16 v[98:113], v[114:117], v[146:149], v[66:81]
	v_add_u32_e32 v139, s21, v241
	ds_read_b128 v[114:117], v139
	v_mfma_f32_32x32x16_bf16 v[82:97], v[118:121], v[150:153], v[82:97]
	ds_read_b128 v[118:121], v139 offset:8192
	s_waitcnt lgkmcnt(0)
	v_mfma_f32_32x32x16_bf16 v[98:113], v[122:125], v[150:153], v[98:113]
	v_add_u32_e32 v139, s21, v242
	ds_read_b128 v[122:125], v139
	v_mfma_f32_32x32x16_bf16 v[82:97], v[114:117], v[154:157], v[82:97]
	ds_read_b128 v[114:117], v139 offset:8192
	v_mfma_f32_32x32x16_bf16 v[98:113], v[118:121], v[154:157], v[98:113]
	s_waitcnt lgkmcnt(0)
	v_mfma_f32_32x32x16_bf16 v[82:97], v[122:125], v[158:161], v[82:97]
	v_mfma_f32_32x32x16_bf16 v[98:113], v[114:117], v[158:161], v[98:113]
	s_nop 0
	ds_read_b128 v[122:125], v212 offset:53248
	ds_read_b128 v[118:121], v212 offset:57344
	ds_read_b128 v[114:117], v212 offset:61440
	s_cmp_le_u32 s20, s16
	s_cbranch_scc1 .LBB0_291
	v_add3_u32 v130, v249, s20, 47
	v_and_b32_e32 v130, 0x3ffffffc, v130
	v_lshl_add_u32 v166, v130, 2, v244
	ds_read_b128 v[130:133], v166
	ds_read_b128 v[134:137], v166 offset:16
	ds_read_b128 v[138:141], v166 offset:64
	ds_read_b128 v[142:145], v166 offset:80
	s_waitcnt lgkmcnt(0)
	v_pk_add_f32 v[84:85], v[84:85], v[132:133]
	v_pk_add_f32 v[88:89], v[88:89], v[136:137]
	v_pk_add_f32 v[92:93], v[92:93], v[140:141]
	v_pk_add_f32 v[96:97], v[96:97], v[144:145]
	v_pk_add_f32 v[94:95], v[94:95], v[142:143]
	v_pk_add_f32 v[90:91], v[90:91], v[138:139]
	v_pk_add_f32 v[86:87], v[86:87], v[134:135]
	v_pk_add_f32 v[82:83], v[82:83], v[130:131]
	ds_read_b128 v[130:133], v166 offset:128
	ds_read_b128 v[134:137], v166 offset:144
	ds_read_b128 v[138:141], v166 offset:192
	ds_read_b128 v[142:145], v166 offset:208
	s_waitcnt lgkmcnt(0)
	v_pk_add_f32 v[100:101], v[100:101], v[132:133]
	v_pk_add_f32 v[104:105], v[104:105], v[136:137]
	v_pk_add_f32 v[108:109], v[108:109], v[140:141]
	v_pk_add_f32 v[112:113], v[112:113], v[144:145]
	v_pk_add_f32 v[110:111], v[110:111], v[142:143]
	v_pk_add_f32 v[106:107], v[106:107], v[138:139]
	v_pk_add_f32 v[102:103], v[102:103], v[134:135]
	v_pk_add_f32 v[98:99], v[98:99], v[130:131]

.LBB0_295:
	s_waitcnt lgkmcnt(3)
	v_mfma_f32_32x32x16_bf16 v[18:33], v[118:121], v[170:173], v[18:33]
	ds_read_b128 v[118:121], v0 offset:57344
	v_exp_f32_e32 v132, v94
	v_exp_f32_e32 v133, v95
	v_add_f32_e32 v130, v130, v132
	v_add_f32_e32 v131, v131, v133
	v_cvt_pk_bf16_f32 v176, v132, v133
	s_waitcnt lgkmcnt(3)
	v_mfma_f32_32x32x16_bf16 v[2:17], v[114:117], v[170:173], v[2:17]
	ds_read_b128 v[114:117], v0 offset:61440
	v_exp_f32_e32 v0, v96
	v_exp_f32_e32 v132, v97
	v_add_f32_e32 v130, v130, v0
	v_add_f32_e32 v131, v131, v132
	v_cvt_pk_bf16_f32 v177, v0, v132
	s_waitcnt lgkmcnt(3)
	v_mfma_f32_32x32x16_bf16 v[50:65], v[126:129], v[178:181], v[50:65]
	v_add_u32_e32 v0, s36, v248
	ds_read_b128 v[126:129], v0 offset:49152
	v_exp_f32_e32 v132, v98
	v_exp_f32_e32 v133, v99
	v_add_f32_e32 v130, v130, v132
	v_add_f32_e32 v131, v131, v133
	v_cvt_pk_bf16_f32 v182, v132, v133
	s_waitcnt lgkmcnt(3)
	v_mfma_f32_32x32x16_bf16 v[34:49], v[122:125], v[178:181], v[34:49]
	v_exp_f32_e32 v132, v100
	v_exp_f32_e32 v133, v101
	ds_read_b128 v[122:125], v0 offset:53248
	v_add_f32_e32 v130, v130, v132
	v_add_f32_e32 v131, v131, v133
	v_cvt_pk_bf16_f32 v183, v132, v133
	s_cmp_eq_u64 s[44:45], 0
	s_cbranch_scc1 .LBB0_297
	s_lshl_b32 s26, s23, 14
	s_add_i32 s26, s10, s26
	s_add_i32 m0, s26, 0xc000
	s_add_u32 s100, s8, s96
	s_addc_u32 s101, s9, s97
	global_load_lds_dwordx4 v216, s[100:101]
.LBB0_297:
	s_waitcnt lgkmcnt(3)
	v_mfma_f32_32x32x16_bf16 v[18:33], v[118:121], v[178:181], v[18:33]
	ds_read_b128 v[118:121], v0 offset:57344
	v_exp_f32_e32 v132, v102
	v_exp_f32_e32 v133, v103
	v_add_f32_e32 v130, v130, v132
	v_add_f32_e32 v131, v131, v133
	v_cvt_pk_bf16_f32 v184, v132, v133
	s_waitcnt lgkmcnt(3)
	v_mfma_f32_32x32x16_bf16 v[2:17], v[114:117], v[178:181], v[2:17]
	ds_read_b128 v[114:117], v0 offset:61440
	v_exp_f32_e32 v0, v104
	v_exp_f32_e32 v132, v105
	v_add_f32_e32 v130, v130, v0
	v_add_f32_e32 v131, v131, v132
	v_cvt_pk_bf16_f32 v185, v0, v132
	s_waitcnt lgkmcnt(3)
	v_mfma_f32_32x32x16_bf16 v[50:65], v[126:129], v[186:189], v[50:65]
	v_exp_f32_e32 v0, v106
	v_exp_f32_e32 v126, v107
	v_add_f32_e32 v127, v130, v0
	v_add_f32_e32 v128, v131, v126
	v_cvt_pk_bf16_f32 v190, v0, v126
	s_waitcnt lgkmcnt(2)
	v_mfma_f32_32x32x16_bf16 v[34:49], v[122:125], v[186:189], v[34:49]
	v_exp_f32_e32 v123, v108
	v_exp_f32_e32 v124, v109
	v_add_f32_e32 v0, v127, v123
	v_add_f32_e32 v122, v128, v124
	s_cmp_eq_u64 s[44:45], 0
	v_cvt_pk_bf16_f32 v191, v123, v124
	s_cbranch_scc1 .LBB0_299
	s_lshl_b32 s26, s23, 14
	s_add_i32 s26, s10, s26
	s_add_i32 m0, s26, 0xe000
	s_add_u32 s100, s8, s58
	s_addc_u32 s101, s9, s59
	global_load_lds_dwordx4 v216, s[100:101]
.LBB0_299:
	s_waitcnt lgkmcnt(1)
	v_mfma_f32_32x32x16_bf16 v[18:33], v[118:121], v[186:189], v[18:33]
	v_exp_f32_e32 v118, v110
	v_exp_f32_e32 v119, v111
	v_add_f32_e32 v0, v0, v118
	v_add_f32_e32 v120, v122, v119
	v_cvt_pk_bf16_f32 v192, v118, v119
	s_waitcnt lgkmcnt(0)
	v_mfma_f32_32x32x16_bf16 v[2:17], v[114:117], v[186:189], v[2:17]
	v_exp_f32_e32 v114, v112
	v_exp_f32_e32 v115, v113
	v_add_f32_e32 v0, v0, v114
	v_add_f32_e32 v116, v120, v115
	v_cvt_pk_bf16_f32 v193, v114, v115
	v_add_f32_e32 v212, v0, v116
	v_cmp_nge_f32_e32 vcc, s7, v212
	s_cbranch_vccnz .Lrare_u2e

.LBB0_303:
	s_cmp_lt_u32 s21, s18
	s_cselect_b64 s[44:45], -1, 0
	s_cmp_ge_u32 s21, s18
	s_cbranch_scc1 .Lotail_u2o

.LBB0_311:
	s_add_i32 s26, s31, 1
	s_cmp_lg_u32 s31, 2
	s_cselect_b32 s31, s26, 0
	s_add_i32 s26, s28, 1
	s_cmp_lg_u32 s28, 2
	s_cselect_b32 s28, s26, 0
	s_add_i32 s26, s33, 1
	s_cmp_lg_u32 s33, 2
	s_cselect_b32 s33, s26, 0
	s_add_i32 s26, s23, 1
	s_lshl_b32 s101, s31, 14
	s_nop 1
	v_add_u32_e32 v82, s101, v239
	v_add_u32_e32 v102, s101, v240
	ds_read_b128 v[98:101], v82
	ds_read_b128 v[114:117], v82 offset:8192
	ds_read_b128 v[118:121], v102
	s_barrier
	s_cmp_lg_u32 s23, 2
	s_cselect_b32 s23, s26, 0
	s_cmp_lt_u32 s22, s19
	s_cbranch_scc0 .Lhd_u2o
.LBB0_317:
	s_lshl_b32 s26, s33, 14
	s_add_i32 s37, s22, 1
	s_add_i32 s36, s26, 0
	s_cmp_ge_u32 s37, s19
	v_add_u32_e32 v212, s36, v245
	v_add_u32_e32 v0, s36, v246
	s_cbranch_scc1 .Lpvo_u2o
.LBB0_328:
	s_lshl_b32 s26, s31, 14
	s_add_i32 s26, s26, 0
	s_nop 1
	ds_read_b128 v[126:129], v212 offset:49152
	s_waitcnt lgkmcnt(1)
	v_mfma_f32_32x32x16_bf16 v[82:97], v[98:101], v[146:149], v[66:81]
	ds_read_b128 v[122:125], v102 offset:8192
	v_mfma_f32_32x32x16_bf16 v[98:113], v[114:117], v[146:149], v[66:81]
	v_add_u32_e32 v139, s26, v241
	ds_read_b128 v[114:117], v139
	v_mfma_f32_32x32x16_bf16 v[82:97], v[118:121], v[150:153], v[82:97]
	ds_read_b128 v[118:121], v139 offset:8192
	s_waitcnt lgkmcnt(0)
	v_mfma_f32_32x32x16_bf16 v[98:113], v[122:125], v[150:153], v[98:113]
	v_add_u32_e32 v139, s26, v242
	ds_read_b128 v[122:125], v139
	v_mfma_f32_32x32x16_bf16 v[82:97], v[114:117], v[154:157], v[82:97]
	ds_read_b128 v[114:117], v139 offset:8192
	v_mfma_f32_32x32x16_bf16 v[98:113], v[118:121], v[154:157], v[98:113]
	s_waitcnt lgkmcnt(0)
	v_mfma_f32_32x32x16_bf16 v[82:97], v[122:125], v[158:161], v[82:97]
	v_mfma_f32_32x32x16_bf16 v[98:113], v[114:117], v[158:161], v[98:113]
	s_nop 0
	ds_read_b128 v[122:125], v212 offset:53248
	ds_read_b128 v[118:121], v212 offset:57344
	ds_read_b128 v[114:117], v212 offset:61440
	s_add_i32 s26, s20, 64
	s_cmp_le_u32 s26, s16
	s_cbranch_scc1 .LBB0_331
	v_add_u32_e32 v130, s20, v249
	v_add_u32_e32 v130, 0x6f, v130
	v_and_b32_e32 v130, 0x3ffffffc, v130
	v_lshl_add_u32 v162, v130, 2, v244
	ds_read_b128 v[130:133], v162
	ds_read_b128 v[134:137], v162 offset:16
	ds_read_b128 v[138:141], v162 offset:64
	ds_read_b128 v[142:145], v162 offset:80
	s_waitcnt lgkmcnt(0)
	v_pk_add_f32 v[84:85], v[84:85], v[132:133]
	v_pk_add_f32 v[86:87], v[86:87], v[134:135]
	v_pk_add_f32 v[90:91], v[90:91], v[138:139]
	v_pk_add_f32 v[94:95], v[94:95], v[142:143]
	v_pk_add_f32 v[96:97], v[96:97], v[144:145]
	v_pk_add_f32 v[92:93], v[92:93], v[140:141]
	v_pk_add_f32 v[88:89], v[88:89], v[136:137]
	v_pk_add_f32 v[82:83], v[82:83], v[130:131]
	ds_read_b128 v[130:133], v162 offset:128
	ds_read_b128 v[134:137], v162 offset:144
	ds_read_b128 v[138:141], v162 offset:192
	ds_read_b128 v[142:145], v162 offset:208
	s_waitcnt lgkmcnt(0)
	v_pk_add_f32 v[100:101], v[100:101], v[132:133]
	v_pk_add_f32 v[102:103], v[102:103], v[134:135]
	v_pk_add_f32 v[106:107], v[106:107], v[138:139]
	v_pk_add_f32 v[110:111], v[110:111], v[142:143]
	v_pk_add_f32 v[112:113], v[112:113], v[144:145]
	v_pk_add_f32 v[108:109], v[108:109], v[140:141]
	v_pk_add_f32 v[104:105], v[104:105], v[136:137]
	v_pk_add_f32 v[98:99], v[98:99], v[130:131]
.LBB0_331:
	s_waitcnt lgkmcnt(3)
	v_mfma_f32_32x32x16_bf16 v[50:65], v[126:129], v[166:169], v[50:65]
	ds_read_b128 v[126:129], v0 offset:49152
	s_nop 0
	v_exp_f32_e32 v130, v82
	v_exp_f32_e32 v131, v83
	v_add_f32_e32 v132, v1, v130
	v_add_f32_e32 v133, v1, v131
	v_cvt_pk_bf16_f32 v162, v130, v131
	s_waitcnt lgkmcnt(3)
	v_mfma_f32_32x32x16_bf16 v[34:49], v[122:125], v[166:169], v[34:49]
	ds_read_b128 v[122:125], v0 offset:53248
	v_exp_f32_e32 v130, v84
	v_exp_f32_e32 v131, v85
	s_add_i32 s22, s22, 3
	s_cmp_le_u32 s22, s17
	v_add_f32_e32 v132, v132, v130
	v_add_f32_e32 v133, v133, v131
	v_cvt_pk_bf16_f32 v163, v130, v131
	s_cselect_b64 s[26:27], -1, 0
	s_cmp_gt_u32 s22, s17
	s_cbranch_scc1 .LBB0_333
	s_lshl_b32 s22, s28, 14
	s_add_u32 s100, s8, s50
	s_addc_u32 s101, s9, s51
	s_add_i32 m0, s10, s22
	s_nop 0
	global_load_lds_dwordx4 v214, s[100:101]
.LBB0_333:
	s_waitcnt lgkmcnt(3)
	v_mfma_f32_32x32x16_bf16 v[18:33], v[118:121], v[166:169], v[18:33]
	ds_read_b128 v[118:121], v0 offset:57344
	v_exp_f32_e32 v134, v86
	v_exp_f32_e32 v135, v87
	v_add_f32_e32 v132, v132, v134
	v_add_f32_e32 v133, v133, v135
	v_cvt_pk_bf16_f32 v164, v134, v135
	s_waitcnt lgkmcnt(3)
	v_mfma_f32_32x32x16_bf16 v[2:17], v[114:117], v[166:169], v[2:17]
	ds_read_b128 v[114:117], v0 offset:61440
	v_exp_f32_e32 v0, v88
	v_exp_f32_e32 v134, v89
	v_add_f32_e32 v132, v132, v0
	v_add_f32_e32 v133, v133, v134
	v_cvt_pk_bf16_f32 v165, v0, v134
	s_waitcnt lgkmcnt(3)
	v_mfma_f32_32x32x16_bf16 v[50:65], v[126:129], v[174:177], v[50:65]
	v_add_u32_e32 v0, s36, v247
	ds_read_b128 v[126:129], v0 offset:49152
	v_exp_f32_e32 v134, v90
	v_exp_f32_e32 v135, v91
	v_add_f32_e32 v132, v132, v134
	v_add_f32_e32 v133, v133, v135
	v_cvt_pk_bf16_f32 v170, v134, v135
	s_waitcnt lgkmcnt(3)
	v_mfma_f32_32x32x16_bf16 v[34:49], v[122:125], v[174:177], v[34:49]
	ds_read_b128 v[122:125], v0 offset:53248
	v_exp_f32_e32 v134, v92
	v_exp_f32_e32 v135, v93
	v_add_f32_e32 v132, v132, v134
	v_add_f32_e32 v133, v133, v135
	s_andn2_b64 vcc, exec, s[26:27]
	v_cvt_pk_bf16_f32 v171, v134, v135
	s_cbranch_vccnz .LBB0_335
	s_lshl_b32 s22, s28, 14
	s_add_i32 s22, s10, s22
	s_add_u32 s100, s8, s4
	s_addc_u32 s101, s9, s5
	s_add_i32 m0, s22, 0x2000
	s_nop 0
	global_load_lds_dwordx4 v214, s[100:101]
.LBB0_335:
	s_waitcnt lgkmcnt(3)
	v_mfma_f32_32x32x16_bf16 v[18:33], v[118:121], v[174:177], v[18:33]
	ds_read_b128 v[118:121], v0 offset:57344
	v_exp_f32_e32 v130, v94
	v_exp_f32_e32 v131, v95
	v_add_f32_e32 v132, v132, v130
	v_add_f32_e32 v133, v133, v131
	v_cvt_pk_bf16_f32 v172, v130, v131
	s_waitcnt lgkmcnt(3)
	v_mfma_f32_32x32x16_bf16 v[2:17], v[114:117], v[174:177], v[2:17]
	ds_read_b128 v[114:117], v0 offset:61440
	v_exp_f32_e32 v0, v96
	v_exp_f32_e32 v130, v97
	v_add_f32_e32 v131, v132, v0
	v_add_f32_e32 v132, v133, v130
	v_cvt_pk_bf16_f32 v173, v0, v130
	s_waitcnt lgkmcnt(3)
	v_mfma_f32_32x32x16_bf16 v[50:65], v[126:129], v[182:185], v[50:65]
	v_add_u32_e32 v0, s36, v248
	ds_read_b128 v[126:129], v0 offset:49152
	v_exp_f32_e32 v130, v98
	v_exp_f32_e32 v133, v99
	v_add_f32_e32 v131, v131, v130
	v_add_f32_e32 v134, v132, v133
	v_cvt_pk_bf16_f32 v178, v130, v133
	s_waitcnt lgkmcnt(3)
	v_mfma_f32_32x32x16_bf16 v[34:49], v[122:125], v[182:185], v[34:49]
	v_exp_f32_e32 v130, v100
	v_exp_f32_e32 v135, v101
	ds_read_b128 v[122:125], v0 offset:53248
	v_add_f32_e32 v132, v131, v130
	v_add_f32_e32 v133, v134, v135
	v_cvt_pk_bf16_f32 v179, v130, v135
	s_cmp_eq_u64 s[44:45], 0
	s_cbranch_scc1 .LBB0_337
	s_lshl_b32 s22, s23, 14
	s_add_i32 s22, s10, s22
	s_add_i32 m0, s22, 0xc000
	s_add_u32 s100, s8, s0
	s_addc_u32 s101, s9, s1
	global_load_lds_dwordx4 v216, s[100:101]
.LBB0_337:
	s_waitcnt lgkmcnt(3)
	v_mfma_f32_32x32x16_bf16 v[18:33], v[118:121], v[182:185], v[18:33]
	ds_read_b128 v[118:121], v0 offset:57344
	v_exp_f32_e32 v134, v102
	v_exp_f32_e32 v135, v103
	v_add_f32_e32 v132, v132, v134
	v_add_f32_e32 v133, v133, v135
	v_cvt_pk_bf16_f32 v180, v134, v135
	s_waitcnt lgkmcnt(3)
	v_mfma_f32_32x32x16_bf16 v[2:17], v[114:117], v[182:185], v[2:17]
	ds_read_b128 v[114:117], v0 offset:61440
	v_exp_f32_e32 v0, v104
	v_exp_f32_e32 v134, v105
	v_add_f32_e32 v132, v132, v0
	v_add_f32_e32 v133, v133, v134
	v_cvt_pk_bf16_f32 v181, v0, v134
	s_waitcnt lgkmcnt(3)
	v_mfma_f32_32x32x16_bf16 v[50:65], v[126:129], v[190:193], v[50:65]
	v_exp_f32_e32 v0, v106
	v_exp_f32_e32 v126, v107
	v_add_f32_e32 v127, v132, v0
	v_add_f32_e32 v128, v133, v126
	v_cvt_pk_bf16_f32 v186, v0, v126
	s_waitcnt lgkmcnt(2)
	v_mfma_f32_32x32x16_bf16 v[34:49], v[122:125], v[190:193], v[34:49]
	v_exp_f32_e32 v123, v108
	v_exp_f32_e32 v124, v109
	v_add_f32_e32 v0, v127, v123
	v_add_f32_e32 v122, v128, v124
	s_cmp_eq_u64 s[44:45], 0
	v_cvt_pk_bf16_f32 v187, v123, v124
	s_cbranch_scc1 .LBB0_339
	s_lshl_b32 s22, s23, 14
	s_add_i32 s22, s10, s22
	s_add_u32 s100, s8, s52
	s_addc_u32 s101, s9, s53
	s_add_i32 m0, s22, 0xe000
	s_nop 0
	global_load_lds_dwordx4 v216, s[100:101]
.LBB0_339:
	s_waitcnt lgkmcnt(1)
	v_mfma_f32_32x32x16_bf16 v[18:33], v[118:121], v[190:193], v[18:33]
	v_exp_f32_e32 v118, v110
	v_exp_f32_e32 v119, v111
	v_add_f32_e32 v0, v0, v118
	v_add_f32_e32 v120, v122, v119
	v_cvt_pk_bf16_f32 v188, v118, v119
	s_waitcnt lgkmcnt(0)
	v_mfma_f32_32x32x16_bf16 v[2:17], v[114:117], v[190:193], v[2:17]
	v_exp_f32_e32 v114, v112
	v_exp_f32_e32 v115, v113
	v_add_f32_e32 v0, v0, v114
	v_add_f32_e32 v116, v120, v115
	v_cvt_pk_bf16_f32 v189, v114, v115
	v_add_f32_e32 v212, v0, v116
	v_cmp_nge_f32_e32 vcc, s7, v212
	s_cbranch_vccnz .Lrare_u2o
.LBB0_341:
	v_add_f32_e32 v243, v212, v243
.LBB0_343:
	s_add_i32 s22, s31, 1
	s_cmp_lg_u32 s31, 2
	s_cselect_b32 s31, s22, 0
	s_add_i32 s22, s28, 1
	s_cmp_lg_u32 s28, 2
	s_cselect_b32 s28, s22, 0
	s_add_i32 s22, s33, 1
	s_cmp_lg_u32 s33, 2
	s_cselect_b32 s33, s22, 0
	s_add_i32 s22, s23, 1
	s_cmp_lg_u32 s23, 2
	s_cselect_b32 s23, s22, 0
	s_addk_i32 s20, 0x80
	s_add_i32 s22, s21, -3
	v_lshl_add_u64 v[214:215], v[214:215], 0, s[34:35]
	s_cmp_ge_u32 s22, s17
	v_lshl_add_u64 v[216:217], v[216:217], 0, s[24:25]
	s_cbranch_scc1 .LBB0_345
	s_mov_b32 s22, s21
	s_branch .LBB0_267
.Lrare_u2e:
	v_max_f32_e32 v0, v99, v99
	v_max_f32_e32 v66, v83, v83
	v_max_f32_e32 v0, v66, v0
	v_max3_f32 v0, v82, v98, v0
	v_max3_f32 v66, v100, v85, v101
	v_max3_f32 v0, v0, v84, v66
	v_max3_f32 v66, v102, v87, v103
	v_max3_f32 v0, v0, v86, v66
	v_max3_f32 v66, v104, v89, v105
	v_max3_f32 v0, v0, v88, v66
	v_max3_f32 v66, v106, v91, v107
	v_max3_f32 v0, v0, v90, v66
	v_max3_f32 v66, v108, v93, v109
	v_max3_f32 v0, v0, v92, v66
	v_max3_f32 v66, v110, v95, v111
	v_max3_f32 v0, v0, v94, v66
	v_max3_f32 v66, v112, v97, v113
	v_max3_f32 v0, v0, v96, v66
	v_mov_b32_e32 v66, v0
	s_nop 1
	v_permlane32_swap_b32_e32 v0, v66
	v_max_f32_e32 v66, v66, v66
	v_max_f32_e32 v0, v0, v0
	v_max_f32_e32 v0, v0, v66
	v_cmp_lt_f32_e32 vcc, s57, v0
	s_nop 1
	v_cndmask_b32_e32 v68, 0, v0, vcc
	v_sub_f32_e32 v0, v82, v68
	v_exp_f32_e32 v116, v0
	v_sub_f32_e32 v0, v98, v68
	v_exp_f32_e32 v117, v0
	v_sub_f32_e32 v0, v83, v68
	v_exp_f32_e32 v118, v0
	v_sub_f32_e32 v0, v99, v68
	v_exp_f32_e32 v119, v0
	v_sub_f32_e32 v0, v84, v68
	v_exp_f32_e32 v98, v0
	v_sub_f32_e32 v0, v100, v68
	v_exp_f32_e32 v82, v0
	v_add_f32_e32 v0, v117, v116
	v_add_f32_e32 v99, 0, v0
	v_add_f32_e32 v83, v119, v118
	v_sub_f32_e32 v0, v85, v68
	v_pk_add_f32 v[66:67], v[82:83], v[98:99]
	v_exp_f32_e32 v83, v0
	v_sub_f32_e32 v0, v101, v68
	v_pk_add_f32 v[114:115], v[66:67], v[66:67] op_sel_hi:[0,1]
	v_exp_f32_e32 v99, v0
	v_sub_f32_e32 v0, v86, v68
	v_exp_f32_e32 v114, v0
	v_sub_f32_e32 v0, v102, v68
	v_exp_f32_e32 v84, v0
	v_add_f32_e32 v85, v99, v83
	v_sub_f32_e32 v0, v87, v68
	v_cvt_pk_bf16_f32 v166, v116, v118
	v_pk_add_f32 v[66:67], v[84:85], v[114:115]
	v_exp_f32_e32 v85, v0
	v_sub_f32_e32 v0, v103, v68
	v_pk_add_f32 v[100:101], v[66:67], v[66:67] op_sel_hi:[0,1]
	v_exp_f32_e32 v115, v0
	v_sub_f32_e32 v0, v88, v68
	v_exp_f32_e32 v100, v0
	v_sub_f32_e32 v0, v104, v68
	v_exp_f32_e32 v86, v0
	v_add_f32_e32 v87, v115, v85
	v_sub_f32_e32 v0, v89, v68
	v_cvt_pk_bf16_f32 v167, v98, v83
	v_pk_add_f32 v[66:67], v[86:87], v[100:101]
	v_exp_f32_e32 v87, v0
	v_sub_f32_e32 v0, v105, v68
	v_pk_add_f32 v[102:103], v[66:67], v[66:67] op_sel_hi:[0,1]
	v_exp_f32_e32 v101, v0
	v_sub_f32_e32 v0, v90, v68
	v_exp_f32_e32 v102, v0
	v_sub_f32_e32 v0, v106, v68
	v_exp_f32_e32 v88, v0
	v_add_f32_e32 v89, v101, v87
	v_sub_f32_e32 v0, v91, v68
	v_cvt_pk_bf16_f32 v168, v114, v85
	v_pk_add_f32 v[66:67], v[88:89], v[102:103]
	v_exp_f32_e32 v89, v0
	v_sub_f32_e32 v0, v107, v68
	v_pk_add_f32 v[104:105], v[66:67], v[66:67] op_sel_hi:[0,1]
	v_exp_f32_e32 v103, v0
	v_sub_f32_e32 v0, v92, v68
	v_exp_f32_e32 v104, v0
	v_sub_f32_e32 v0, v108, v68
	v_exp_f32_e32 v90, v0
	v_sub_f32_e32 v0, v97, v68
	v_exp_f32_e32 v97, v0
	v_add_f32_e32 v91, v103, v89
	v_sub_f32_e32 v0, v93, v68
	v_pk_add_f32 v[66:67], v[90:91], v[104:105]
	v_exp_f32_e32 v91, v0
	v_sub_f32_e32 v0, v109, v68
	v_pk_add_f32 v[106:107], v[66:67], v[66:67] op_sel_hi:[0,1]
	v_exp_f32_e32 v105, v0
	v_sub_f32_e32 v0, v94, v68
	v_exp_f32_e32 v106, v0
	v_sub_f32_e32 v0, v110, v68
	v_exp_f32_e32 v92, v0
	v_sub_f32_e32 v0, v113, v68
	v_exp_f32_e32 v110, v0
	v_add_f32_e32 v93, v105, v91
	v_sub_f32_e32 v0, v95, v68
	v_pk_add_f32 v[66:67], v[92:93], v[106:107]
	v_exp_f32_e32 v93, v0
	v_sub_f32_e32 v0, v111, v68
	v_pk_add_f32 v[108:109], v[66:67], v[66:67] op_sel_hi:[0,1]
	v_exp_f32_e32 v107, v0
	v_sub_f32_e32 v0, v96, v68
	v_exp_f32_e32 v108, v0
	v_sub_f32_e32 v0, v112, v68
	v_exp_f32_e32 v94, v0
	v_add_f32_e32 v95, v107, v93
	v_exp_f32_e64 v0, -v68
	v_add_f32_e32 v212, v110, v97
	v_pk_add_f32 v[66:67], v[94:95], v[108:109]
	v_cvt_pk_bf16_f32 v169, v100, v87
	v_pk_add_f32 v[66:67], v[66:67], v[66:67] op_sel:[0,1] op_sel_hi:[1,0]
	v_pk_mul_f32 v[64:65], v[64:65], v[0:1] op_sel_hi:[1,0]
	v_mov_b32_e32 v67, v68
	v_pk_add_f32 v[212:213], v[212:213], v[66:67]
	v_pk_mul_f32 v[62:63], v[62:63], v[0:1] op_sel_hi:[1,0]
	v_xor_b32_e32 v66, 0x80000000, v213
	v_mov_b32_e32 v67, v66
	v_mov_b32_e32 v68, v66
	v_mov_b32_e32 v69, v66
	v_mov_b32_e32 v70, v66
	v_mov_b32_e32 v71, v66
	v_mov_b32_e32 v72, v66
	v_mov_b32_e32 v73, v66
	v_mov_b32_e32 v74, v66
	v_mov_b32_e32 v75, v66
	v_mov_b32_e32 v76, v66
	v_mov_b32_e32 v77, v66
	v_mov_b32_e32 v78, v66
	v_mov_b32_e32 v79, v66
	v_mov_b32_e32 v80, v66
	v_mov_b32_e32 v81, v66
	v_pk_mul_f32 v[60:61], v[60:61], v[0:1] op_sel_hi:[1,0]
	v_pk_mul_f32 v[58:59], v[58:59], v[0:1] op_sel_hi:[1,0]
	v_pk_mul_f32 v[56:57], v[56:57], v[0:1] op_sel_hi:[1,0]
	v_pk_mul_f32 v[54:55], v[54:55], v[0:1] op_sel_hi:[1,0]
	v_pk_mul_f32 v[52:53], v[52:53], v[0:1] op_sel_hi:[1,0]
	v_pk_mul_f32 v[50:51], v[50:51], v[0:1] op_sel_hi:[1,0]
	v_pk_mul_f32 v[48:49], v[48:49], v[0:1] op_sel_hi:[1,0]
	v_pk_mul_f32 v[46:47], v[46:47], v[0:1] op_sel_hi:[1,0]
	v_pk_mul_f32 v[44:45], v[44:45], v[0:1] op_sel_hi:[1,0]
	v_pk_mul_f32 v[42:43], v[42:43], v[0:1] op_sel_hi:[1,0]
	v_pk_mul_f32 v[40:41], v[40:41], v[0:1] op_sel_hi:[1,0]
	v_pk_mul_f32 v[38:39], v[38:39], v[0:1] op_sel_hi:[1,0]
	v_pk_mul_f32 v[36:37], v[36:37], v[0:1] op_sel_hi:[1,0]
	v_pk_mul_f32 v[34:35], v[34:35], v[0:1] op_sel_hi:[1,0]
	v_pk_mul_f32 v[32:33], v[32:33], v[0:1] op_sel_hi:[1,0]
	v_pk_mul_f32 v[30:31], v[30:31], v[0:1] op_sel_hi:[1,0]
	v_pk_mul_f32 v[28:29], v[28:29], v[0:1] op_sel_hi:[1,0]
	v_pk_mul_f32 v[26:27], v[26:27], v[0:1] op_sel_hi:[1,0]
	v_pk_mul_f32 v[24:25], v[24:25], v[0:1] op_sel_hi:[1,0]
	v_pk_mul_f32 v[22:23], v[22:23], v[0:1] op_sel_hi:[1,0]
	v_pk_mul_f32 v[20:21], v[20:21], v[0:1] op_sel_hi:[1,0]
	v_pk_mul_f32 v[18:19], v[18:19], v[0:1] op_sel_hi:[1,0]
	v_pk_mul_f32 v[16:17], v[16:17], v[0:1] op_sel_hi:[1,0]
	v_pk_mul_f32 v[14:15], v[14:15], v[0:1] op_sel_hi:[1,0]
	v_pk_mul_f32 v[12:13], v[12:13], v[0:1] op_sel_hi:[1,0]
	v_pk_mul_f32 v[10:11], v[10:11], v[0:1] op_sel_hi:[1,0]
	v_pk_mul_f32 v[8:9], v[8:9], v[0:1] op_sel_hi:[1,0]
	v_pk_mul_f32 v[6:7], v[6:7], v[0:1] op_sel_hi:[1,0]
	v_pk_mul_f32 v[4:5], v[4:5], v[0:1] op_sel_hi:[1,0]
	v_pk_mul_f32 v[2:3], v[2:3], v[0:1] op_sel_hi:[1,0]
	v_mul_f32_e32 v243, v243, v0
	v_cvt_pk_bf16_f32 v174, v102, v89
	v_cvt_pk_bf16_f32 v175, v104, v91
	v_cvt_pk_bf16_f32 v176, v106, v93
	v_cvt_pk_bf16_f32 v177, v108, v97
	v_cvt_pk_bf16_f32 v182, v117, v119
	v_cvt_pk_bf16_f32 v183, v82, v99
	v_cvt_pk_bf16_f32 v184, v84, v115
	v_cvt_pk_bf16_f32 v185, v86, v101
	v_cvt_pk_bf16_f32 v190, v88, v103
	v_cvt_pk_bf16_f32 v191, v90, v105
	v_cvt_pk_bf16_f32 v192, v92, v107
	v_cvt_pk_bf16_f32 v193, v94, v110
	s_branch .LBB0_301
.LBB0_302:
	s_nop 3
	v_mov_b64_e32 v[50:51], v[82:83]
	v_mov_b64_e32 v[34:35], v[98:99]
	s_nop 1
	v_mov_b64_e32 v[18:19], v[114:115]
	v_mov_b64_e32 v[2:3], v[130:131]
	v_mov_b64_e32 v[52:53], v[84:85]
	v_mov_b64_e32 v[54:55], v[86:87]
	v_mov_b64_e32 v[56:57], v[88:89]
	v_mov_b64_e32 v[58:59], v[90:91]
	v_mov_b64_e32 v[60:61], v[92:93]
	v_mov_b64_e32 v[62:63], v[94:95]
	v_mov_b64_e32 v[64:65], v[96:97]
	v_mov_b64_e32 v[36:37], v[100:101]
	v_mov_b64_e32 v[38:39], v[102:103]
	v_mov_b64_e32 v[40:41], v[104:105]
	v_mov_b64_e32 v[42:43], v[106:107]
	v_mov_b64_e32 v[44:45], v[108:109]
	v_mov_b64_e32 v[46:47], v[110:111]
	v_mov_b64_e32 v[48:49], v[112:113]
	v_mov_b64_e32 v[20:21], v[116:117]
	v_mov_b64_e32 v[22:23], v[118:119]
	v_mov_b64_e32 v[24:25], v[120:121]
	v_mov_b64_e32 v[26:27], v[122:123]
	v_mov_b64_e32 v[28:29], v[124:125]
	v_mov_b64_e32 v[30:31], v[126:127]
	v_mov_b64_e32 v[32:33], v[128:129]
	v_mov_b64_e32 v[4:5], v[132:133]
	v_mov_b64_e32 v[6:7], v[134:135]
	v_mov_b64_e32 v[8:9], v[136:137]
	v_mov_b64_e32 v[10:11], v[138:139]
	v_mov_b64_e32 v[12:13], v[140:141]
	v_mov_b64_e32 v[14:15], v[142:143]
	v_mov_b64_e32 v[16:17], v[144:145]
	s_branch .LBB0_303
.Lhd_u2e:
	s_add_i32 s21, s22, 2
	s_cmp_ge_u32 s21, s18
	s_cbranch_scc1 .LBB0_274
	s_lshl_b32 s26, s28, 14
	s_add_i32 s26, s10, s26
	s_add_i32 s27, s26, 0x2000
	s_mov_b32 m0, s26
	s_add_u32 s100, s8, s80
	s_addc_u32 s101, s9, s81
	global_load_lds_dwordx4 v214, s[100:101]
	s_mov_b32 m0, s27
	s_add_u32 s100, s8, s62
	s_addc_u32 s101, s9, s63
	global_load_lds_dwordx4 v214, s[100:101]

.Lpvo_u2e:
	s_mov_b64 s[26:27], -1
	ds_read_b128 v[98:101], v212 offset:49152
	ds_read_b128 v[114:117], v212 offset:53248
	ds_read_b128 v[130:133], v212 offset:57344
	ds_read_b128 v[194:197], v212 offset:61440
	s_waitcnt lgkmcnt(0)
	v_mfma_f32_32x32x16_bf16 v[82:97], v[98:101], v[162:165], v[50:65]
	ds_read_b128 v[206:209], v0 offset:49152
	v_mfma_f32_32x32x16_bf16 v[98:113], v[114:117], v[162:165], v[34:49]
	ds_read_b128 v[198:201], v0 offset:53248
	s_add_i32 s21, s22, 2
	s_cmp_lt_u32 s21, s18
	s_cselect_b64 s[26:27], -1, 0
	s_cmp_ge_u32 s21, s18
	s_cbranch_scc1 .LBB0_281
	s_lshl_b32 s37, s28, 14
	s_add_i32 m0, s10, s37
	s_add_u32 s100, s8, s80
	s_addc_u32 s101, s9, s81
	global_load_lds_dwordx4 v214, s[100:101]

.Lrare_u2o:
	v_max_f32_e32 v0, v99, v99
	v_max_f32_e32 v66, v83, v83
	v_max_f32_e32 v0, v66, v0
	v_max3_f32 v0, v82, v98, v0
	v_max3_f32 v66, v100, v85, v101
	v_max3_f32 v0, v0, v84, v66
	v_max3_f32 v66, v102, v87, v103
	v_max3_f32 v0, v0, v86, v66
	v_max3_f32 v66, v104, v89, v105
	v_max3_f32 v0, v0, v88, v66
	v_max3_f32 v66, v106, v91, v107
	v_max3_f32 v0, v0, v90, v66
	v_max3_f32 v66, v108, v93, v109
	v_max3_f32 v0, v0, v92, v66
	v_max3_f32 v66, v110, v95, v111
	v_max3_f32 v0, v0, v94, v66
	v_max3_f32 v66, v112, v97, v113
	v_max3_f32 v0, v0, v96, v66
	v_mov_b32_e32 v66, v0
	s_nop 1
	v_permlane32_swap_b32_e32 v0, v66
	v_max_f32_e32 v66, v66, v66
	v_max_f32_e32 v0, v0, v0
	v_max_f32_e32 v0, v0, v66
	v_cmp_lt_f32_e32 vcc, s57, v0
	s_nop 1
	v_cndmask_b32_e32 v68, 0, v0, vcc
	v_sub_f32_e32 v0, v82, v68
	v_exp_f32_e32 v116, v0
	v_sub_f32_e32 v0, v98, v68
	v_exp_f32_e32 v117, v0
	v_sub_f32_e32 v0, v83, v68
	v_exp_f32_e32 v118, v0
	v_sub_f32_e32 v0, v99, v68
	v_exp_f32_e32 v119, v0
	v_sub_f32_e32 v0, v84, v68
	v_exp_f32_e32 v114, v0
	v_sub_f32_e32 v0, v100, v68
	v_exp_f32_e32 v82, v0
	v_add_f32_e32 v0, v116, v117
	v_add_f32_e32 v83, 0, v0
	v_add_f32_e32 v115, v118, v119
	v_sub_f32_e32 v0, v85, v68
	v_pk_add_f32 v[66:67], v[114:115], v[82:83]
	v_exp_f32_e32 v83, v0
	v_sub_f32_e32 v0, v101, v68
	v_exp_f32_e32 v115, v0
	v_sub_f32_e32 v0, v86, v68
	v_pk_add_f32 v[98:99], v[66:67], v[66:67] op_sel_hi:[0,1]
	v_exp_f32_e32 v100, v0
	v_sub_f32_e32 v0, v102, v68
	v_exp_f32_e32 v98, v0
	v_add_f32_e32 v101, v83, v115
	v_sub_f32_e32 v0, v87, v68
	v_cvt_pk_bf16_f32 v162, v116, v118
	v_pk_add_f32 v[66:67], v[100:101], v[98:99]
	v_exp_f32_e32 v99, v0
	v_sub_f32_e32 v0, v103, v68
	v_exp_f32_e32 v101, v0
	v_sub_f32_e32 v0, v88, v68
	v_pk_add_f32 v[84:85], v[66:67], v[66:67] op_sel_hi:[0,1]
	v_exp_f32_e32 v102, v0
	v_sub_f32_e32 v0, v104, v68
	v_exp_f32_e32 v84, v0
	v_add_f32_e32 v103, v99, v101
	v_sub_f32_e32 v0, v89, v68
	v_cvt_pk_bf16_f32 v163, v114, v83
	v_pk_add_f32 v[66:67], v[102:103], v[84:85]
	v_exp_f32_e32 v85, v0
	v_sub_f32_e32 v0, v105, v68
	v_exp_f32_e32 v103, v0
	v_sub_f32_e32 v0, v90, v68
	v_pk_add_f32 v[86:87], v[66:67], v[66:67] op_sel_hi:[0,1]
	v_exp_f32_e32 v104, v0
	v_sub_f32_e32 v0, v106, v68
	v_exp_f32_e32 v86, v0
	v_add_f32_e32 v105, v85, v103
	v_sub_f32_e32 v0, v91, v68
	v_cvt_pk_bf16_f32 v164, v100, v99
	v_pk_add_f32 v[66:67], v[104:105], v[86:87]
	v_exp_f32_e32 v87, v0
	v_sub_f32_e32 v0, v107, v68
	v_exp_f32_e32 v105, v0
	v_sub_f32_e32 v0, v92, v68
	v_pk_add_f32 v[88:89], v[66:67], v[66:67] op_sel_hi:[0,1]
	v_exp_f32_e32 v90, v0
	v_sub_f32_e32 v0, v108, v68
	v_exp_f32_e32 v88, v0
	v_sub_f32_e32 v0, v97, v68
	v_exp_f32_e32 v97, v0
	v_add_f32_e32 v91, v87, v105
	v_sub_f32_e32 v0, v93, v68
	v_pk_add_f32 v[66:67], v[90:91], v[88:89]
	v_exp_f32_e32 v89, v0
	v_sub_f32_e32 v0, v109, v68
	v_exp_f32_e32 v91, v0
	v_sub_f32_e32 v0, v94, v68
	v_pk_add_f32 v[106:107], v[66:67], v[66:67] op_sel_hi:[0,1]
	v_exp_f32_e32 v92, v0
	v_sub_f32_e32 v0, v110, v68
	v_exp_f32_e32 v106, v0
	v_sub_f32_e32 v0, v113, v68
	v_exp_f32_e32 v110, v0
	v_add_f32_e32 v93, v89, v91
	v_sub_f32_e32 v0, v95, v68
	v_pk_add_f32 v[66:67], v[92:93], v[106:107]
	v_exp_f32_e32 v93, v0
	v_sub_f32_e32 v0, v111, v68
	v_exp_f32_e32 v107, v0
	v_sub_f32_e32 v0, v96, v68
	v_pk_add_f32 v[108:109], v[66:67], v[66:67] op_sel_hi:[0,1]
	v_exp_f32_e32 v94, v0
	v_sub_f32_e32 v0, v112, v68
	v_exp_f32_e32 v108, v0
	v_add_f32_e32 v95, v93, v107
	v_exp_f32_e64 v0, -v68
	v_add_f32_e32 v212, v97, v110
	v_pk_add_f32 v[66:67], v[94:95], v[108:109]
	v_cvt_pk_bf16_f32 v165, v102, v85
	v_pk_add_f32 v[66:67], v[66:67], v[66:67] op_sel:[0,1] op_sel_hi:[1,0]
	v_pk_mul_f32 v[64:65], v[64:65], v[0:1] op_sel_hi:[1,0]
	v_mov_b32_e32 v67, v68
	v_pk_add_f32 v[212:213], v[212:213], v[66:67]
	v_pk_mul_f32 v[62:63], v[62:63], v[0:1] op_sel_hi:[1,0]
	v_xor_b32_e32 v66, 0x80000000, v213
	v_mov_b32_e32 v67, v66
	v_mov_b32_e32 v68, v66
	v_mov_b32_e32 v69, v66
	v_mov_b32_e32 v70, v66
	v_mov_b32_e32 v71, v66
	v_mov_b32_e32 v72, v66
	v_mov_b32_e32 v73, v66
	v_mov_b32_e32 v74, v66
	v_mov_b32_e32 v75, v66
	v_mov_b32_e32 v76, v66
	v_mov_b32_e32 v77, v66
	v_mov_b32_e32 v78, v66
	v_mov_b32_e32 v79, v66
	v_mov_b32_e32 v80, v66
	v_mov_b32_e32 v81, v66
	v_pk_mul_f32 v[60:61], v[60:61], v[0:1] op_sel_hi:[1,0]
	v_pk_mul_f32 v[58:59], v[58:59], v[0:1] op_sel_hi:[1,0]
	v_pk_mul_f32 v[56:57], v[56:57], v[0:1] op_sel_hi:[1,0]
	v_pk_mul_f32 v[54:55], v[54:55], v[0:1] op_sel_hi:[1,0]
	v_pk_mul_f32 v[52:53], v[52:53], v[0:1] op_sel_hi:[1,0]
	v_pk_mul_f32 v[50:51], v[50:51], v[0:1] op_sel_hi:[1,0]
	v_pk_mul_f32 v[48:49], v[48:49], v[0:1] op_sel_hi:[1,0]
	v_pk_mul_f32 v[46:47], v[46:47], v[0:1] op_sel_hi:[1,0]
	v_pk_mul_f32 v[44:45], v[44:45], v[0:1] op_sel_hi:[1,0]
	v_pk_mul_f32 v[42:43], v[42:43], v[0:1] op_sel_hi:[1,0]
	v_pk_mul_f32 v[40:41], v[40:41], v[0:1] op_sel_hi:[1,0]
	v_pk_mul_f32 v[38:39], v[38:39], v[0:1] op_sel_hi:[1,0]
	v_pk_mul_f32 v[36:37], v[36:37], v[0:1] op_sel_hi:[1,0]
	v_pk_mul_f32 v[34:35], v[34:35], v[0:1] op_sel_hi:[1,0]
	v_pk_mul_f32 v[32:33], v[32:33], v[0:1] op_sel_hi:[1,0]
	v_pk_mul_f32 v[30:31], v[30:31], v[0:1] op_sel_hi:[1,0]
	v_pk_mul_f32 v[28:29], v[28:29], v[0:1] op_sel_hi:[1,0]
	v_pk_mul_f32 v[26:27], v[26:27], v[0:1] op_sel_hi:[1,0]
	v_pk_mul_f32 v[24:25], v[24:25], v[0:1] op_sel_hi:[1,0]
	v_pk_mul_f32 v[22:23], v[22:23], v[0:1] op_sel_hi:[1,0]
	v_pk_mul_f32 v[20:21], v[20:21], v[0:1] op_sel_hi:[1,0]
	v_pk_mul_f32 v[18:19], v[18:19], v[0:1] op_sel_hi:[1,0]
	v_pk_mul_f32 v[16:17], v[16:17], v[0:1] op_sel_hi:[1,0]
	v_pk_mul_f32 v[14:15], v[14:15], v[0:1] op_sel_hi:[1,0]
	v_pk_mul_f32 v[12:13], v[12:13], v[0:1] op_sel_hi:[1,0]
	v_pk_mul_f32 v[10:11], v[10:11], v[0:1] op_sel_hi:[1,0]
	v_pk_mul_f32 v[8:9], v[8:9], v[0:1] op_sel_hi:[1,0]
	v_pk_mul_f32 v[6:7], v[6:7], v[0:1] op_sel_hi:[1,0]
	v_pk_mul_f32 v[4:5], v[4:5], v[0:1] op_sel_hi:[1,0]
	v_pk_mul_f32 v[2:3], v[2:3], v[0:1] op_sel_hi:[1,0]
	v_mul_f32_e32 v243, v243, v0
	v_cvt_pk_bf16_f32 v170, v104, v87
	v_cvt_pk_bf16_f32 v171, v90, v89
	v_cvt_pk_bf16_f32 v172, v92, v93
	v_cvt_pk_bf16_f32 v173, v94, v97
	v_cvt_pk_bf16_f32 v178, v117, v119
	v_cvt_pk_bf16_f32 v179, v82, v115
	v_cvt_pk_bf16_f32 v180, v98, v101
	v_cvt_pk_bf16_f32 v181, v84, v103
	v_cvt_pk_bf16_f32 v186, v86, v105
	v_cvt_pk_bf16_f32 v187, v88, v91
	v_cvt_pk_bf16_f32 v188, v106, v107
	v_cvt_pk_bf16_f32 v189, v108, v110
	s_branch .LBB0_341

.Lhd_u2o:
	s_add_i32 s26, s22, 3
	s_cmp_gt_u32 s26, s17
	s_cbranch_scc1 .LBB0_314
	s_lshl_b32 s26, s28, 14
	s_add_i32 s26, s10, s26
	s_add_i32 s27, s26, 0x2000
	s_mov_b32 m0, s26
	s_add_u32 s100, s8, s50
	s_addc_u32 s101, s9, s51
	global_load_lds_dwordx4 v214, s[100:101]
	s_mov_b32 m0, s27
	s_add_u32 s100, s8, s4
	s_addc_u32 s101, s9, s5
	global_load_lds_dwordx4 v214, s[100:101]

.Lpvo_u2o:
	s_mov_b64 s[26:27], -1
	ds_read_b128 v[98:101], v212 offset:49152
	ds_read_b128 v[114:117], v212 offset:53248
	ds_read_b128 v[130:133], v212 offset:57344
	ds_read_b128 v[194:197], v212 offset:61440
	s_waitcnt lgkmcnt(0)
	v_mfma_f32_32x32x16_bf16 v[82:97], v[98:101], v[166:169], v[50:65]
	ds_read_b128 v[206:209], v0 offset:49152
	v_mfma_f32_32x32x16_bf16 v[98:113], v[114:117], v[166:169], v[34:49]
	ds_read_b128 v[198:201], v0 offset:53248
	s_add_i32 s37, s22, 3
	s_cmp_le_u32 s37, s17
	s_cselect_b64 s[26:27], -1, 0
	s_cmp_gt_u32 s37, s17
	s_cbranch_scc1 .LBB0_321
	s_lshl_b32 s37, s28, 14
	s_add_i32 m0, s10, s37
	s_add_u32 s100, s8, s50
	s_addc_u32 s101, s9, s51
	global_load_lds_dwordx4 v214, s[100:101]

.Lotail_u2o:
	s_cmp_eq_u64 s[38:39], 0
	s_cbranch_scc1 .Low2_u2o
	s_waitcnt vmcnt(0)
	s_branch .LBB0_311
